# non-temporal hint on read-once loads in P0 (f32 weights), mlstm_b, mlstm_c and the latent phase
# speedup vs baseline: 1.0138x; 1.0091x over previous
.LBB0_74:
	v_lshrrev_b32_e32 v1, 3, v136
	v_lshlrev_b32_e32 v2, 2, v136
	v_and_b32_e32 v135, 28, v2
	v_lshl_or_b32 v47, s83, 6, v1
	v_mov_b32_e32 v2, 0
	s_lshl_b32 s10, s82, 6
	v_mov_b32_e32 v4, v2
	v_mov_b32_e32 v5, v2
	v_ashrrev_i32_e32 v6, 31, v47
	v_or_b32_e32 v34, s10, v135
	v_mov_b32_e32 v3, v2
	v_mul_lo_u32 v66, s6, v6
	v_mov_b64_e32 v[8:9], v[4:5]
	v_mov_b64_e32 v[12:13], v[4:5]
	s_ashr_i32 s11, s10, 31
	v_cmp_gt_i32_e32 vcc, s14, v34
	v_mul_lo_u32 v48, s7, v47
	v_lshlrev_b32_e32 v138, 2, v135
	v_or_b32_e32 v46, 8, v47
	v_mov_b64_e32 v[6:7], v[2:3]
	v_mov_b64_e32 v[10:11], v[2:3]
	s_and_saveexec_b64 s[12:13], vcc
	s_cbranch_execz .LBB0_76
	v_mad_u64_u32 v[6:7], s[22:23], s6, v47, 0
	v_add3_u32 v7, v7, v66, v48
	s_ashr_i32 s9, s8, 31
	s_waitcnt lgkmcnt(0)
	v_lshl_add_u64 v[6:7], v[6:7], 2, s[4:5]
	s_lshl_b64 s[22:23], s[8:9], 2
	v_lshl_add_u64 v[6:7], v[6:7], 0, s[22:23]
	s_lshl_b64 s[24:25], s[10:11], 2
	v_lshl_add_u64 v[6:7], v[6:7], 0, s[24:25]
	v_mov_b32_e32 v139, v2
	v_lshl_add_u64 v[14:15], v[6:7], 0, v[138:139]
	v_mul_lo_u32 v8, s7, v46
	v_mad_u64_u32 v[6:7], s[26:27], s6, v46, 0
	v_add3_u32 v7, v7, v66, v8
	v_lshl_add_u64 v[6:7], v[6:7], 2, s[4:5]
	v_lshl_add_u64 v[6:7], v[6:7], 0, s[22:23]
	v_lshl_add_u64 v[6:7], v[6:7], 0, s[24:25]
	v_lshl_add_u64 v[16:17], v[6:7], 0, v[138:139]
	global_load_dwordx4 v[6:9], v[14:15], off nt
	global_load_dwordx4 v[10:13], v[16:17], off nt
.LBB0_76:
	s_or_b64 exec, exec, s[12:13]
	v_mov_b64_e32 v[16:17], v[4:5]
	v_or_b32_e32 v51, 16, v47
	v_or_b32_e32 v50, 24, v47
	v_mov_b64_e32 v[14:15], v[2:3]
	s_and_saveexec_b64 s[12:13], vcc
	s_cbranch_execz .LBB0_78
	v_mul_lo_u32 v4, s7, v51
	v_mad_u64_u32 v[2:3], s[22:23], s6, v51, 0
	v_add3_u32 v3, v3, v66, v4
	s_ashr_i32 s9, s8, 31
	s_waitcnt lgkmcnt(0)
	v_lshl_add_u64 v[2:3], v[2:3], 2, s[4:5]
	s_lshl_b64 s[22:23], s[8:9], 2
	v_lshl_add_u64 v[2:3], v[2:3], 0, s[22:23]
	s_lshl_b64 s[24:25], s[10:11], 2
	v_lshl_add_u64 v[2:3], v[2:3], 0, s[24:25]
	v_mov_b32_e32 v139, 0
	v_lshl_add_u64 v[18:19], v[2:3], 0, v[138:139]
	v_mul_lo_u32 v4, s7, v50
	v_mad_u64_u32 v[2:3], s[26:27], s6, v50, 0
	v_add3_u32 v3, v3, v66, v4
	v_lshl_add_u64 v[2:3], v[2:3], 2, s[4:5]
	v_lshl_add_u64 v[2:3], v[2:3], 0, s[22:23]
	v_lshl_add_u64 v[2:3], v[2:3], 0, s[24:25]
	v_lshl_add_u64 v[20:21], v[2:3], 0, v[138:139]
	global_load_dwordx4 v[2:5], v[18:19], off nt
	global_load_dwordx4 v[14:17], v[20:21], off nt
.LBB0_78:
	s_or_b64 exec, exec, s[12:13]
	v_mov_b32_e32 v18, 0
	v_mov_b32_e32 v20, v18
	v_mov_b32_e32 v21, v18
	v_mov_b32_e32 v19, v18
	v_mov_b64_e32 v[24:25], v[20:21]
	v_mov_b64_e32 v[28:29], v[20:21]
	v_or_b32_e32 v63, 32, v47
	v_or_b32_e32 v62, 40, v47
	v_mov_b64_e32 v[22:23], v[18:19]
	v_mov_b64_e32 v[26:27], v[18:19]
	s_and_saveexec_b64 s[12:13], vcc
	s_cbranch_execz .LBB0_80
	v_mul_lo_u32 v24, s7, v63
	v_mad_u64_u32 v[22:23], s[22:23], s6, v63, 0
	v_add3_u32 v23, v23, v66, v24
	s_ashr_i32 s9, s8, 31
	s_waitcnt lgkmcnt(0)
	v_lshl_add_u64 v[22:23], v[22:23], 2, s[4:5]
	s_lshl_b64 s[22:23], s[8:9], 2
	v_lshl_add_u64 v[22:23], v[22:23], 0, s[22:23]
	s_lshl_b64 s[24:25], s[10:11], 2
	v_lshl_add_u64 v[22:23], v[22:23], 0, s[24:25]
	v_mov_b32_e32 v139, v18
	v_lshl_add_u64 v[30:31], v[22:23], 0, v[138:139]
	v_mul_lo_u32 v24, s7, v62
	v_mad_u64_u32 v[22:23], s[26:27], s6, v62, 0
	v_add3_u32 v23, v23, v66, v24
	v_lshl_add_u64 v[22:23], v[22:23], 2, s[4:5]
	v_lshl_add_u64 v[22:23], v[22:23], 0, s[22:23]
	v_lshl_add_u64 v[22:23], v[22:23], 0, s[24:25]
	v_lshl_add_u64 v[32:33], v[22:23], 0, v[138:139]
	global_load_dwordx4 v[22:25], v[30:31], off nt
	global_load_dwordx4 v[26:29], v[32:33], off nt
.LBB0_80:
	s_or_b64 exec, exec, s[12:13]
	v_mov_b64_e32 v[32:33], v[20:21]
	v_or_b32_e32 v68, 48, v47
	v_or_b32_e32 v67, 56, v47
	v_mov_b64_e32 v[30:31], v[18:19]
	s_and_saveexec_b64 s[12:13], vcc
	s_cbranch_execz .LBB0_82
	v_mul_lo_u32 v20, s7, v68
	v_mad_u64_u32 v[18:19], s[22:23], s6, v68, 0
	v_add3_u32 v19, v19, v66, v20
	s_ashr_i32 s9, s8, 31
	s_waitcnt lgkmcnt(0)
	v_lshl_add_u64 v[18:19], v[18:19], 2, s[4:5]
	s_lshl_b64 s[22:23], s[8:9], 2
	v_lshl_add_u64 v[18:19], v[18:19], 0, s[22:23]
	s_lshl_b64 s[24:25], s[10:11], 2
	v_lshl_add_u64 v[18:19], v[18:19], 0, s[24:25]
	v_mov_b32_e32 v139, 0
	v_lshl_add_u64 v[36:37], v[18:19], 0, v[138:139]
	v_mul_lo_u32 v20, s7, v67
	v_mad_u64_u32 v[18:19], s[26:27], s6, v67, 0
	v_add3_u32 v19, v19, v66, v20
	v_lshl_add_u64 v[18:19], v[18:19], 2, s[4:5]
	v_lshl_add_u64 v[18:19], v[18:19], 0, s[22:23]
	v_lshl_add_u64 v[18:19], v[18:19], 0, s[24:25]
	v_lshl_add_u64 v[38:39], v[18:19], 0, v[138:139]
	global_load_dwordx4 v[18:21], v[36:37], off nt
	global_load_dwordx4 v[30:33], v[38:39], off nt
.LBB0_82:
	s_or_b64 exec, exec, s[12:13]
	v_or_b32_e32 v34, 32, v34
	v_cmp_gt_i32_e32 vcc, s14, v34
	v_mov_b32_e32 v34, 0
	v_mov_b32_e32 v36, v34
	v_mov_b32_e32 v37, v34
	v_mov_b32_e32 v35, v34
	v_mov_b64_e32 v[40:41], v[36:37]
	v_mov_b64_e32 v[44:45], v[36:37]
	v_mov_b64_e32 v[38:39], v[34:35]
	v_mov_b64_e32 v[42:43], v[34:35]
	s_and_saveexec_b64 s[12:13], vcc
	s_cbranch_execz .LBB0_84
	v_mad_u64_u32 v[38:39], s[14:15], s6, v47, 0
	v_add3_u32 v39, v39, v66, v48
	s_ashr_i32 s9, s8, 31
	s_waitcnt lgkmcnt(0)
	v_lshl_add_u64 v[38:39], v[38:39], 2, s[4:5]
	s_lshl_b64 s[14:15], s[8:9], 2
	v_lshl_add_u64 v[38:39], v[38:39], 0, s[14:15]
	s_lshl_b64 s[22:23], s[10:11], 2
	v_lshl_add_u64 v[38:39], v[38:39], 0, s[22:23]
	v_mov_b32_e32 v139, v34
	v_lshl_add_u64 v[48:49], v[38:39], 0, v[138:139]
	v_mul_lo_u32 v40, s7, v46
	v_mad_u64_u32 v[38:39], s[24:25], s6, v46, 0
	v_add3_u32 v39, v39, v66, v40
	v_lshl_add_u64 v[38:39], v[38:39], 2, s[4:5]
	v_lshl_add_u64 v[38:39], v[38:39], 0, s[14:15]
	v_lshl_add_u64 v[38:39], v[38:39], 0, s[22:23]
	v_lshl_add_u64 v[46:47], v[38:39], 0, v[138:139]
	global_load_dwordx4 v[38:41], v[48:49], off offset:128 nt
	global_load_dwordx4 v[42:45], v[46:47], off offset:128 nt
.LBB0_84:
	s_or_b64 exec, exec, s[12:13]
	v_mov_b64_e32 v[48:49], v[36:37]
	v_mov_b64_e32 v[46:47], v[34:35]
	s_and_saveexec_b64 s[12:13], vcc
	s_cbranch_execz .LBB0_86
	v_mul_lo_u32 v36, s7, v51
	v_mad_u64_u32 v[34:35], s[14:15], s6, v51, 0
	v_add3_u32 v35, v35, v66, v36
	s_ashr_i32 s9, s8, 31
	s_waitcnt lgkmcnt(0)
	v_lshl_add_u64 v[34:35], v[34:35], 2, s[4:5]
	s_lshl_b64 s[14:15], s[8:9], 2
	v_lshl_add_u64 v[34:35], v[34:35], 0, s[14:15]
	s_lshl_b64 s[22:23], s[10:11], 2
	v_lshl_add_u64 v[34:35], v[34:35], 0, s[22:23]
	v_mov_b32_e32 v139, 0
	v_lshl_add_u64 v[52:53], v[34:35], 0, v[138:139]
	v_mul_lo_u32 v36, s7, v50
	v_mad_u64_u32 v[34:35], s[24:25], s6, v50, 0
	v_add3_u32 v35, v35, v66, v36
	v_lshl_add_u64 v[34:35], v[34:35], 2, s[4:5]
	v_lshl_add_u64 v[34:35], v[34:35], 0, s[14:15]
	v_lshl_add_u64 v[34:35], v[34:35], 0, s[22:23]
	v_lshl_add_u64 v[50:51], v[34:35], 0, v[138:139]
	global_load_dwordx4 v[34:37], v[52:53], off offset:128 nt
	global_load_dwordx4 v[46:49], v[50:51], off offset:128 nt
.LBB0_86:
	s_or_b64 exec, exec, s[12:13]
	v_mov_b32_e32 v50, 0
	v_mov_b32_e32 v52, v50
	v_mov_b32_e32 v53, v50
	v_mov_b32_e32 v51, v50
	v_mov_b64_e32 v[56:57], v[52:53]
	v_mov_b64_e32 v[60:61], v[52:53]
	v_mov_b64_e32 v[54:55], v[50:51]
	v_mov_b64_e32 v[58:59], v[50:51]
	s_and_saveexec_b64 s[12:13], vcc
	s_cbranch_execz .LBB0_88
	v_mul_lo_u32 v56, s7, v63
	v_mad_u64_u32 v[54:55], s[14:15], s6, v63, 0
	v_add3_u32 v55, v55, v66, v56
	s_ashr_i32 s9, s8, 31
	s_waitcnt lgkmcnt(0)
	v_lshl_add_u64 v[54:55], v[54:55], 2, s[4:5]
	s_lshl_b64 s[14:15], s[8:9], 2
	v_lshl_add_u64 v[54:55], v[54:55], 0, s[14:15]
	s_lshl_b64 s[22:23], s[10:11], 2
	v_lshl_add_u64 v[54:55], v[54:55], 0, s[22:23]
	v_mov_b32_e32 v139, v50
	v_lshl_add_u64 v[64:65], v[54:55], 0, v[138:139]
	v_mul_lo_u32 v56, s7, v62
	v_mad_u64_u32 v[54:55], s[24:25], s6, v62, 0
	v_add3_u32 v55, v55, v66, v56
	v_lshl_add_u64 v[54:55], v[54:55], 2, s[4:5]
	v_lshl_add_u64 v[54:55], v[54:55], 0, s[14:15]
	v_lshl_add_u64 v[54:55], v[54:55], 0, s[22:23]
	v_lshl_add_u64 v[62:63], v[54:55], 0, v[138:139]
	global_load_dwordx4 v[54:57], v[64:65], off offset:128 nt
	global_load_dwordx4 v[58:61], v[62:63], off offset:128 nt
.LBB0_88:
	s_or_b64 exec, exec, s[12:13]
	v_mov_b64_e32 v[64:65], v[52:53]
	v_mov_b64_e32 v[62:63], v[50:51]
	s_and_saveexec_b64 s[12:13], vcc
	s_cbranch_execz .LBB0_90
	v_mul_lo_u32 v52, s7, v68
	v_mad_u64_u32 v[50:51], s[14:15], s6, v68, 0
	v_add3_u32 v51, v51, v66, v52
	s_ashr_i32 s9, s8, 31
	s_waitcnt lgkmcnt(0)
	v_lshl_add_u64 v[50:51], v[50:51], 2, s[4:5]
	s_lshl_b64 s[8:9], s[8:9], 2
	v_lshl_add_u64 v[50:51], v[50:51], 0, s[8:9]
	s_lshl_b64 s[10:11], s[10:11], 2
	v_lshl_add_u64 v[50:51], v[50:51], 0, s[10:11]
	v_mov_b32_e32 v139, 0
	v_lshl_add_u64 v[68:69], v[50:51], 0, v[138:139]
	v_mul_lo_u32 v52, s7, v67
	v_mad_u64_u32 v[50:51], s[6:7], s6, v67, 0
	v_add3_u32 v51, v51, v66, v52
	v_lshl_add_u64 v[50:51], v[50:51], 2, s[4:5]
	v_lshl_add_u64 v[50:51], v[50:51], 0, s[8:9]
	v_lshl_add_u64 v[50:51], v[50:51], 0, s[10:11]
	v_lshl_add_u64 v[66:67], v[50:51], 0, v[138:139]
	global_load_dwordx4 v[50:53], v[68:69], off offset:128 nt
	global_load_dwordx4 v[62:65], v[66:67], off offset:128 nt

.LBB0_152:
	s_lshl_b32 s70, s91, 6
	v_mov_b32_e32 v68, v66
	v_mov_b32_e32 v69, v66
	v_or_b32_e32 v102, s70, v135
	v_lshl_or_b32 v111, s89, 6, v1
	v_mov_b32_e32 v67, v66
	v_mov_b64_e32 v[76:77], v[68:69]
	v_mov_b64_e32 v[72:73], v[68:69]
	s_ashr_i32 s71, s70, 31
	v_cmp_gt_i32_e32 vcc, s33, v102
	v_or_b32_e32 v110, 8, v111
	v_mov_b64_e32 v[74:75], v[66:67]
	v_mov_b64_e32 v[70:71], v[66:67]
	s_and_saveexec_b64 s[72:73], vcc
	s_cbranch_execz .LBB0_154
	v_mad_i64_i32 v[70:71], s[74:75], s53, v111, 0
	s_ashr_i32 s69, s68, 31
	v_mad_i64_i32 v[72:73], s[92:93], s53, v110, 0
	s_waitcnt lgkmcnt(0)
	v_lshl_add_u64 v[70:71], v[70:71], 2, s[64:65]
	s_lshl_b64 s[74:75], s[68:69], 2
	v_lshl_add_u64 v[72:73], v[72:73], 2, s[64:65]
	v_lshl_add_u64 v[70:71], v[70:71], 0, s[74:75]
	s_lshl_b64 s[76:77], s[70:71], 2
	v_lshl_add_u64 v[72:73], v[72:73], 0, s[74:75]
	v_lshl_add_u64 v[70:71], v[70:71], 0, s[76:77]
	v_mov_b32_e32 v139, v66
	v_lshl_add_u64 v[72:73], v[72:73], 0, s[76:77]
	v_lshl_add_u64 v[70:71], v[70:71], 0, v[138:139]
	v_lshl_add_u64 v[72:73], v[72:73], 0, v[138:139]
	global_load_dwordx4 v[74:77], v[70:71], off nt
	s_nop 0
	global_load_dwordx4 v[70:73], v[72:73], off nt
.LBB0_154:
	s_or_b64 exec, exec, s[72:73]
	v_mov_b64_e32 v[80:81], v[68:69]
	v_mov_b64_e32 v[84:85], v[68:69]
	v_or_b32_e32 v119, 16, v111
	v_or_b32_e32 v118, 24, v111
	v_mov_b64_e32 v[78:79], v[66:67]
	v_mov_b64_e32 v[82:83], v[66:67]
	s_and_saveexec_b64 s[72:73], vcc
	s_cbranch_execz .LBB0_156
	v_mad_i64_i32 v[68:69], s[74:75], s53, v119, 0
	s_ashr_i32 s69, s68, 31
	v_mad_i64_i32 v[78:79], s[92:93], s53, v118, 0
	s_waitcnt lgkmcnt(0)
	v_lshl_add_u64 v[68:69], v[68:69], 2, s[64:65]
	s_lshl_b64 s[74:75], s[68:69], 2
	v_lshl_add_u64 v[78:79], v[78:79], 2, s[64:65]
	v_lshl_add_u64 v[68:69], v[68:69], 0, s[74:75]
	s_lshl_b64 s[76:77], s[70:71], 2
	v_lshl_add_u64 v[78:79], v[78:79], 0, s[74:75]
	v_lshl_add_u64 v[68:69], v[68:69], 0, s[76:77]
	v_mov_b32_e32 v139, v66
	v_lshl_add_u64 v[78:79], v[78:79], 0, s[76:77]
	v_lshl_add_u64 v[68:69], v[68:69], 0, v[138:139]
	v_lshl_add_u64 v[82:83], v[78:79], 0, v[138:139]
	global_load_dwordx4 v[78:81], v[68:69], off nt
	s_nop 0
	global_load_dwordx4 v[82:85], v[82:83], off nt
.LBB0_156:
	s_or_b64 exec, exec, s[72:73]
	v_mov_b32_e32 v68, v66
	v_mov_b32_e32 v69, v66
	v_mov_b32_e32 v67, v66
	v_mov_b64_e32 v[88:89], v[68:69]
	v_mov_b64_e32 v[92:93], v[68:69]
	v_or_b32_e32 v127, 32, v111
	v_or_b32_e32 v126, 40, v111
	v_mov_b64_e32 v[86:87], v[66:67]
	v_mov_b64_e32 v[90:91], v[66:67]
	s_and_saveexec_b64 s[72:73], vcc
	s_cbranch_execz .LBB0_158
	v_mad_i64_i32 v[86:87], s[74:75], s53, v127, 0
	s_ashr_i32 s69, s68, 31
	v_mad_i64_i32 v[88:89], s[92:93], s53, v126, 0
	s_waitcnt lgkmcnt(0)
	v_lshl_add_u64 v[86:87], v[86:87], 2, s[64:65]
	s_lshl_b64 s[74:75], s[68:69], 2
	v_lshl_add_u64 v[88:89], v[88:89], 2, s[64:65]
	v_lshl_add_u64 v[86:87], v[86:87], 0, s[74:75]
	s_lshl_b64 s[76:77], s[70:71], 2
	v_lshl_add_u64 v[88:89], v[88:89], 0, s[74:75]
	v_lshl_add_u64 v[86:87], v[86:87], 0, s[76:77]
	v_mov_b32_e32 v139, v66
	v_lshl_add_u64 v[88:89], v[88:89], 0, s[76:77]
	v_lshl_add_u64 v[86:87], v[86:87], 0, v[138:139]
	v_lshl_add_u64 v[90:91], v[88:89], 0, v[138:139]
	global_load_dwordx4 v[86:89], v[86:87], off nt
	s_nop 0
	global_load_dwordx4 v[90:93], v[90:91], off nt
.LBB0_158:
	s_or_b64 exec, exec, s[72:73]
	v_mov_b64_e32 v[96:97], v[68:69]
	v_mov_b64_e32 v[100:101], v[68:69]
	v_or_b32_e32 v146, 48, v111
	v_or_b32_e32 v141, 56, v111
	v_mov_b64_e32 v[94:95], v[66:67]
	v_mov_b64_e32 v[98:99], v[66:67]
	s_and_saveexec_b64 s[72:73], vcc
	s_cbranch_execz .LBB0_160
	v_mad_i64_i32 v[68:69], s[74:75], s53, v146, 0
	s_ashr_i32 s69, s68, 31
	v_mad_i64_i32 v[94:95], s[92:93], s53, v141, 0
	s_waitcnt lgkmcnt(0)
	v_lshl_add_u64 v[68:69], v[68:69], 2, s[64:65]
	s_lshl_b64 s[74:75], s[68:69], 2
	v_lshl_add_u64 v[94:95], v[94:95], 2, s[64:65]
	v_lshl_add_u64 v[68:69], v[68:69], 0, s[74:75]
	s_lshl_b64 s[76:77], s[70:71], 2
	v_lshl_add_u64 v[94:95], v[94:95], 0, s[74:75]
	v_lshl_add_u64 v[68:69], v[68:69], 0, s[76:77]
	v_mov_b32_e32 v139, v66
	v_lshl_add_u64 v[94:95], v[94:95], 0, s[76:77]
	v_lshl_add_u64 v[68:69], v[68:69], 0, v[138:139]
	v_lshl_add_u64 v[98:99], v[94:95], 0, v[138:139]
	global_load_dwordx4 v[94:97], v[68:69], off nt
	s_nop 0
	global_load_dwordx4 v[98:101], v[98:99], off nt
.LBB0_160:
	s_or_b64 exec, exec, s[72:73]
	v_or_b32_e32 v67, 32, v102
	v_mov_b32_e32 v68, v66
	v_mov_b32_e32 v69, v66
	v_cmp_gt_i32_e32 vcc, s33, v67
	v_mov_b32_e32 v67, v66
	v_mov_b64_e32 v[104:105], v[68:69]
	v_mov_b64_e32 v[108:109], v[68:69]
	v_mov_b64_e32 v[102:103], v[66:67]
	v_mov_b64_e32 v[106:107], v[66:67]
	s_and_saveexec_b64 s[72:73], vcc
	s_cbranch_execz .LBB0_162
	v_mad_i64_i32 v[102:103], s[74:75], s53, v111, 0
	s_ashr_i32 s69, s68, 31
	v_mad_i64_i32 v[104:105], s[92:93], s53, v110, 0
	s_waitcnt lgkmcnt(0)
	v_lshl_add_u64 v[102:103], v[102:103], 2, s[64:65]
	s_lshl_b64 s[74:75], s[68:69], 2
	v_lshl_add_u64 v[104:105], v[104:105], 2, s[64:65]
	v_lshl_add_u64 v[102:103], v[102:103], 0, s[74:75]
	s_lshl_b64 s[76:77], s[70:71], 2
	v_lshl_add_u64 v[104:105], v[104:105], 0, s[74:75]
	v_lshl_add_u64 v[102:103], v[102:103], 0, s[76:77]
	v_mov_b32_e32 v139, v66
	v_lshl_add_u64 v[104:105], v[104:105], 0, s[76:77]
	v_lshl_add_u64 v[102:103], v[102:103], 0, v[138:139]
	v_lshl_add_u64 v[106:107], v[104:105], 0, v[138:139]
	global_load_dwordx4 v[102:105], v[102:103], off offset:128 nt
	s_nop 0
	global_load_dwordx4 v[106:109], v[106:107], off offset:128 nt
.LBB0_162:
	s_or_b64 exec, exec, s[72:73]
	v_mov_b64_e32 v[112:113], v[68:69]
	v_mov_b64_e32 v[116:117], v[68:69]
	v_mov_b64_e32 v[110:111], v[66:67]
	v_mov_b64_e32 v[114:115], v[66:67]
	s_and_saveexec_b64 s[72:73], vcc
	s_cbranch_execz .LBB0_164
	v_mad_i64_i32 v[68:69], s[74:75], s53, v119, 0
	s_ashr_i32 s69, s68, 31
	v_mad_i64_i32 v[110:111], s[92:93], s53, v118, 0
	s_waitcnt lgkmcnt(0)
	v_lshl_add_u64 v[68:69], v[68:69], 2, s[64:65]
	s_lshl_b64 s[74:75], s[68:69], 2
	v_lshl_add_u64 v[110:111], v[110:111], 2, s[64:65]
	v_lshl_add_u64 v[68:69], v[68:69], 0, s[74:75]
	s_lshl_b64 s[76:77], s[70:71], 2
	v_lshl_add_u64 v[110:111], v[110:111], 0, s[74:75]
	v_lshl_add_u64 v[68:69], v[68:69], 0, s[76:77]
	v_mov_b32_e32 v139, v66
	v_lshl_add_u64 v[110:111], v[110:111], 0, s[76:77]
	v_lshl_add_u64 v[68:69], v[68:69], 0, v[138:139]
	v_lshl_add_u64 v[114:115], v[110:111], 0, v[138:139]
	global_load_dwordx4 v[110:113], v[68:69], off offset:128 nt
	s_nop 0
	global_load_dwordx4 v[114:117], v[114:115], off offset:128 nt
.LBB0_164:
	s_or_b64 exec, exec, s[72:73]
	v_mov_b32_e32 v68, v66
	v_mov_b32_e32 v69, v66
	v_mov_b32_e32 v67, v66
	v_mov_b64_e32 v[120:121], v[68:69]
	v_mov_b64_e32 v[124:125], v[68:69]
	v_mov_b64_e32 v[118:119], v[66:67]
	v_mov_b64_e32 v[122:123], v[66:67]
	s_and_saveexec_b64 s[72:73], vcc
	s_cbranch_execz .LBB0_166
	v_mad_i64_i32 v[118:119], s[74:75], s53, v127, 0
	s_ashr_i32 s69, s68, 31
	v_mad_i64_i32 v[120:121], s[92:93], s53, v126, 0
	s_waitcnt lgkmcnt(0)
	v_lshl_add_u64 v[118:119], v[118:119], 2, s[64:65]
	s_lshl_b64 s[74:75], s[68:69], 2
	v_lshl_add_u64 v[120:121], v[120:121], 2, s[64:65]
	v_lshl_add_u64 v[118:119], v[118:119], 0, s[74:75]
	s_lshl_b64 s[76:77], s[70:71], 2
	v_lshl_add_u64 v[120:121], v[120:121], 0, s[74:75]
	v_lshl_add_u64 v[118:119], v[118:119], 0, s[76:77]
	v_mov_b32_e32 v139, v66
	v_lshl_add_u64 v[120:121], v[120:121], 0, s[76:77]
	v_lshl_add_u64 v[118:119], v[118:119], 0, v[138:139]
	v_lshl_add_u64 v[122:123], v[120:121], 0, v[138:139]
	global_load_dwordx4 v[118:121], v[118:119], off offset:128 nt
	s_nop 0
	global_load_dwordx4 v[122:125], v[122:123], off offset:128 nt
.LBB0_166:
	s_or_b64 exec, exec, s[72:73]
	v_mov_b64_e32 v[128:129], v[68:69]
	v_mov_b64_e32 v[132:133], v[68:69]
	v_mov_b64_e32 v[126:127], v[66:67]
	v_mov_b64_e32 v[130:131], v[66:67]
	s_and_saveexec_b64 s[72:73], vcc
	s_cbranch_execz .LBB0_168
	v_mad_i64_i32 v[68:69], s[74:75], s53, v146, 0
	s_ashr_i32 s69, s68, 31
	v_mad_i64_i32 v[126:127], s[76:77], s53, v141, 0
	s_waitcnt lgkmcnt(0)
	v_lshl_add_u64 v[68:69], v[68:69], 2, s[64:65]
	s_lshl_b64 s[74:75], s[68:69], 2
	v_lshl_add_u64 v[126:127], v[126:127], 2, s[64:65]
	v_lshl_add_u64 v[68:69], v[68:69], 0, s[74:75]
	s_lshl_b64 s[70:71], s[70:71], 2
	v_lshl_add_u64 v[126:127], v[126:127], 0, s[74:75]
	v_lshl_add_u64 v[68:69], v[68:69], 0, s[70:71]
	v_mov_b32_e32 v139, v66
	v_lshl_add_u64 v[126:127], v[126:127], 0, s[70:71]
	v_lshl_add_u64 v[68:69], v[68:69], 0, v[138:139]
	v_lshl_add_u64 v[130:131], v[126:127], 0, v[138:139]
	global_load_dwordx4 v[126:129], v[68:69], off offset:128 nt
	s_nop 0
	global_load_dwordx4 v[130:133], v[130:131], off offset:128 nt

.LBB0_173:
	global_load_dword v5, v[2:3], off nt
	v_add_u32_e32 v1, 0x200, v1
	v_cmp_lt_i32_e32 vcc, s10, v1
	s_or_b64 s[6:7], vcc, s[6:7]
	v_lshl_add_u64 v[2:3], v[2:3], 0, s[8:9]
	s_waitcnt vmcnt(0)
	v_mul_f32_e32 v6, 0xbfb8aa3b, v5
	v_exp_f32_e32 v6, v6
	s_nop 0
	v_add_f32_e32 v6, 1.0, v6
	v_div_scale_f32 v7, s[12:13], v6, v6, v5
	v_rcp_f32_e32 v8, v7
	v_div_scale_f32 v9, vcc, v5, v6, v5
	v_fma_f32 v10, -v7, v8, 1.0
	v_fmac_f32_e32 v8, v10, v8
	v_mul_f32_e32 v10, v9, v8
	v_fma_f32 v11, -v7, v10, v9
	v_fmac_f32_e32 v10, v11, v8
	v_fma_f32 v7, -v7, v10, v9
	v_div_fmas_f32 v7, v7, v8, v10
	v_div_fixup_f32 v5, v7, v6, v5
	ds_write_b32 v4, v5
	v_add_u32_e32 v4, 0x800, v4
	s_andn2_b64 exec, exec, s[6:7]
	s_cbranch_execnz .LBB0_173

.LBB0_186:
	global_load_dword v12, v[6:7], off nt
	s_add_i32 s43, s40, s42
	v_lshl_add_u64 v[14:15], v[6:7], 0, s[38:39]
	v_mov_b32_e32 v135, s43
	global_load_dword v146, v[14:15], off nt
	v_lshl_add_u64 v[30:31], v[14:15], 0, s[38:39]
	ds_read_b128 v[14:17], v135
	ds_read_b128 v[18:21], v135 offset:16
	ds_read_b128 v[22:25], v135 offset:32
	ds_read_b128 v[26:29], v135 offset:48
	global_load_dword v148, v[30:31], off nt
	v_lshl_add_u64 v[150:151], v[30:31], 0, s[38:39]
	v_lshl_add_u64 v[152:153], v[150:151], 0, s[38:39]
	ds_read_b128 v[30:33], v135 offset:4096
	ds_read_b128 v[34:37], v135 offset:4112
	ds_read_b128 v[38:41], v135 offset:8192
	ds_read_b128 v[42:45], v135 offset:8208
	ds_read_b128 v[46:49], v135 offset:12288
	ds_read_b128 v[50:53], v135 offset:12304
	ds_read_b128 v[54:57], v135 offset:4128
	ds_read_b128 v[58:61], v135 offset:4144
	ds_read_b128 v[62:65], v135 offset:8224
	ds_read_b128 v[66:69], v135 offset:8240
	ds_read_b128 v[70:73], v135 offset:12320
	ds_read_b128 v[74:77], v135 offset:12336
	ds_read_b128 v[78:81], v135 offset:64
	ds_read_b128 v[82:85], v135 offset:80
	ds_read_b128 v[86:89], v135 offset:4160
	ds_read_b128 v[90:93], v135 offset:4176
	ds_read_b128 v[94:97], v135 offset:8256
	ds_read_b128 v[98:101], v135 offset:8272
	ds_read_b128 v[102:105], v135 offset:12352
	ds_read_b128 v[106:109], v135 offset:12368
	ds_read_b128 v[110:113], v135 offset:96
	ds_read_b128 v[114:117], v135 offset:112
	ds_read_b128 v[118:121], v135 offset:4192
	ds_read_b128 v[122:125], v135 offset:4208
	ds_read_b128 v[126:129], v135 offset:8288
	ds_read_b128 v[130:133], v135 offset:8304
	ds_read_b128 v[138:141], v135 offset:12384
	ds_read_b128 v[142:145], v135 offset:12400
	global_load_dword v150, v[150:151], off nt
	s_nop 0
	global_load_dword v154, v[152:153], off nt
	v_lshl_add_u64 v[152:153], v[152:153], 0, s[38:39]
	v_lshl_add_u64 v[156:157], v[152:153], 0, s[38:39]
	global_load_dword v152, v[152:153], off nt
	s_nop 0
	global_load_dword v158, v[156:157], off nt
	v_lshl_add_u64 v[156:157], v[156:157], 0, s[38:39]
	s_waitcnt lgkmcnt(14)
	v_mov_b32_e32 v160, v30
	v_mov_b32_e32 v162, v46
	v_mov_b32_e32 v163, v38
	v_mov_b32_e32 v38, v47
	v_mov_b32_e32 v30, v32
	v_mov_b32_e32 v46, v48
	v_mov_b32_e32 v47, v40
	v_mov_b32_e32 v40, v49
	v_mov_b32_e32 v32, v34
	v_mov_b32_e32 v48, v50
	v_mov_b32_e32 v49, v42
	v_mov_b32_e32 v42, v51
	v_mov_b32_e32 v34, v36
	v_mov_b32_e32 v50, v52
	v_mov_b32_e32 v51, v44
	global_load_dword v36, v[156:157], off nt
	v_mov_b32_e32 v44, v53
	v_lshl_add_u64 v[52:53], v[156:157], 0, s[38:39]
	v_mov_b32_e32 v156, v54
	v_mov_b32_e32 v54, v56
	v_mov_b32_e32 v56, v58
	v_mov_b32_e32 v58, v60
	s_waitcnt lgkmcnt(13)
	v_mov_b32_e32 v60, v86
	v_mov_b32_e32 v86, v88
	s_waitcnt lgkmcnt(12)
	v_mov_b32_e32 v88, v90
	v_mov_b32_e32 v90, v92
	s_waitcnt lgkmcnt(5)
	v_mov_b32_e32 v92, v118
	v_mov_b32_e32 v118, v120
	global_load_dword v120, v[52:53], off nt
	v_lshl_add_u64 v[52:53], v[52:53], 0, s[38:39]
	v_mov_b32_e32 v164, v70
	v_mov_b32_e32 v70, v72
	v_mov_b32_e32 v72, v74
	v_mov_b32_e32 v74, v76
	v_mov_b32_e32 v76, v102
	v_mov_b32_e32 v102, v104
	v_mov_b32_e32 v104, v106
	v_mov_b32_e32 v106, v108
	s_waitcnt lgkmcnt(1)
	v_mov_b32_e32 v108, v138
	global_load_dword v138, v[52:53], off nt
	v_lshl_add_u64 v[52:53], v[52:53], 0, s[38:39]
	global_load_dword v166, v[52:53], off nt
	v_lshl_add_u64 v[52:53], v[52:53], 0, s[38:39]
	global_load_dword v168, v[52:53], off nt
	v_lshl_add_u64 v[52:53], v[52:53], 0, s[38:39]
	global_load_dword v170, v[52:53], off nt
	v_lshl_add_u64 v[52:53], v[52:53], 0, s[38:39]
	global_load_dword v172, v[52:53], off nt
	v_lshl_add_u64 v[52:53], v[52:53], 0, s[38:39]
	global_load_dword v174, v[52:53], off nt
	v_lshl_add_u64 v[52:53], v[52:53], 0, s[38:39]
	global_load_dword v176, v[52:53], off nt
	v_lshl_add_u64 v[52:53], v[52:53], 0, s[38:39]
	global_load_dword v178, v[52:53], off nt
	v_lshl_add_u64 v[52:53], v[52:53], 0, s[38:39]
	global_load_dword v180, v[52:53], off nt
	v_lshl_add_u64 v[52:53], v[52:53], 0, s[38:39]
	global_load_dword v182, v[52:53], off nt
	v_lshl_add_u64 v[52:53], v[52:53], 0, s[38:39]
	global_load_dword v184, v[52:53], off nt
	v_lshl_add_u64 v[52:53], v[52:53], 0, s[38:39]
	global_load_dword v186, v[52:53], off nt
	v_lshl_add_u64 v[52:53], v[52:53], 0, s[38:39]
	global_load_dword v188, v[52:53], off nt
	v_lshl_add_u64 v[52:53], v[52:53], 0, s[38:39]
	global_load_dword v192, v[52:53], off nt
	v_lshl_add_u64 v[52:53], v[52:53], 0, s[38:39]
	global_load_dword v194, v[52:53], off nt
	v_lshl_add_u64 v[52:53], v[52:53], 0, s[38:39]
	global_load_dword v196, v[52:53], off nt
	v_lshl_add_u64 v[52:53], v[52:53], 0, s[38:39]
	global_load_dword v198, v[52:53], off nt
	v_lshl_add_u64 v[52:53], v[52:53], 0, s[38:39]
	global_load_dword v200, v[52:53], off nt
	v_lshl_add_u64 v[52:53], v[52:53], 0, s[38:39]
	global_load_dword v202, v[52:53], off nt
	v_lshl_add_u64 v[52:53], v[52:53], 0, s[38:39]
	global_load_dword v204, v[52:53], off nt
	v_lshl_add_u64 v[52:53], v[52:53], 0, s[38:39]
	global_load_dword v206, v[52:53], off nt
	v_lshl_add_u64 v[52:53], v[52:53], 0, s[38:39]
	global_load_dword v208, v[52:53], off nt
	v_lshl_add_u64 v[52:53], v[52:53], 0, s[38:39]
	global_load_dword v52, v[52:53], off nt
	v_mov_b32_e32 v161, v14
	v_mov_b32_e32 v14, v31
	s_waitcnt vmcnt(31)
	v_pk_fma_f32 v[10:11], v[12:13], v[160:161], v[10:11] op_sel_hi:[0,1,1]
	v_pk_fma_f32 v[8:9], v[12:13], v[162:163], v[8:9] op_sel_hi:[0,1,1]
	v_mov_b32_e32 v31, v16
	s_waitcnt vmcnt(30)
	v_pk_fma_f32 v[10:11], v[146:147], v[14:15], v[10:11] op_sel_hi:[0,1,1]
	v_pk_fma_f32 v[8:9], v[146:147], v[38:39], v[8:9] op_sel_hi:[0,1,1]
	v_mov_b32_e32 v16, v33
	s_waitcnt vmcnt(29)
	v_pk_fma_f32 v[10:11], v[148:149], v[30:31], v[10:11] op_sel_hi:[0,1,1]
	v_pk_fma_f32 v[8:9], v[148:149], v[46:47], v[8:9] op_sel_hi:[0,1,1]
	v_mov_b32_e32 v33, v18
	s_waitcnt vmcnt(28)
	v_pk_fma_f32 v[10:11], v[150:151], v[16:17], v[10:11] op_sel_hi:[0,1,1]
	v_pk_fma_f32 v[8:9], v[150:151], v[40:41], v[8:9] op_sel_hi:[0,1,1]
	v_mov_b32_e32 v18, v35
	s_waitcnt vmcnt(27)
	v_pk_fma_f32 v[10:11], v[154:155], v[32:33], v[10:11] op_sel_hi:[0,1,1]
	v_pk_fma_f32 v[8:9], v[154:155], v[48:49], v[8:9] op_sel_hi:[0,1,1]
	v_mov_b32_e32 v35, v20
	s_waitcnt vmcnt(26)
	v_pk_fma_f32 v[10:11], v[152:153], v[18:19], v[10:11] op_sel_hi:[0,1,1]
	v_pk_fma_f32 v[8:9], v[152:153], v[42:43], v[8:9] op_sel_hi:[0,1,1]
	v_mov_b32_e32 v20, v37
	s_waitcnt vmcnt(25)
	v_pk_fma_f32 v[10:11], v[158:159], v[34:35], v[10:11] op_sel_hi:[0,1,1]
	v_pk_fma_f32 v[8:9], v[158:159], v[50:51], v[8:9] op_sel_hi:[0,1,1]
	v_mov_b32_e32 v157, v22
	v_mov_b32_e32 v165, v62
	s_waitcnt vmcnt(24)
	v_pk_fma_f32 v[10:11], v[36:37], v[20:21], v[10:11] op_sel_hi:[0,1,1]
	v_pk_fma_f32 v[8:9], v[36:37], v[44:45], v[8:9] op_sel_hi:[0,1,1]
	v_mov_b32_e32 v22, v55
	v_mov_b32_e32 v62, v71
	s_waitcnt vmcnt(23)
	v_pk_fma_f32 v[10:11], v[120:121], v[156:157], v[10:11] op_sel_hi:[0,1,1]
	v_pk_fma_f32 v[8:9], v[120:121], v[164:165], v[8:9] op_sel_hi:[0,1,1]
	v_mov_b32_e32 v55, v24
	v_mov_b32_e32 v71, v64
	v_mov_b32_e32 v24, v57
	v_mov_b32_e32 v64, v73
	v_mov_b32_e32 v57, v26
	s_waitcnt vmcnt(22)
	v_pk_fma_f32 v[10:11], v[138:139], v[22:23], v[10:11] op_sel_hi:[0,1,1]
	v_pk_fma_f32 v[8:9], v[138:139], v[62:63], v[8:9] op_sel_hi:[0,1,1]
	s_waitcnt vmcnt(21)
	v_pk_fma_f32 v[10:11], v[166:167], v[54:55], v[10:11] op_sel_hi:[0,1,1]
	v_pk_fma_f32 v[8:9], v[166:167], v[70:71], v[8:9] op_sel_hi:[0,1,1]
	v_mov_b32_e32 v73, v66
	s_waitcnt vmcnt(20)
	v_pk_fma_f32 v[10:11], v[168:169], v[24:25], v[10:11] op_sel_hi:[0,1,1]
	v_pk_fma_f32 v[8:9], v[168:169], v[64:65], v[8:9] op_sel_hi:[0,1,1]
	v_mov_b32_e32 v26, v59
	v_mov_b32_e32 v66, v75
	s_waitcnt vmcnt(19)
	v_pk_fma_f32 v[10:11], v[170:171], v[56:57], v[10:11] op_sel_hi:[0,1,1]
	v_pk_fma_f32 v[8:9], v[170:171], v[72:73], v[8:9] op_sel_hi:[0,1,1]
	v_mov_b32_e32 v59, v28
	v_mov_b32_e32 v75, v68
	s_waitcnt vmcnt(18)
	v_pk_fma_f32 v[10:11], v[172:173], v[26:27], v[10:11] op_sel_hi:[0,1,1]
	v_pk_fma_f32 v[8:9], v[172:173], v[66:67], v[8:9] op_sel_hi:[0,1,1]
	v_mov_b32_e32 v28, v61
	v_mov_b32_e32 v68, v77
	s_waitcnt vmcnt(17)
	v_pk_fma_f32 v[10:11], v[174:175], v[58:59], v[10:11] op_sel_hi:[0,1,1]
	v_pk_fma_f32 v[8:9], v[174:175], v[74:75], v[8:9] op_sel_hi:[0,1,1]
	v_mov_b32_e32 v61, v78
	v_mov_b32_e32 v77, v94
	s_waitcnt vmcnt(16)
	v_pk_fma_f32 v[10:11], v[176:177], v[28:29], v[10:11] op_sel_hi:[0,1,1]
	v_pk_fma_f32 v[8:9], v[176:177], v[68:69], v[8:9] op_sel_hi:[0,1,1]
	v_mov_b32_e32 v78, v87
	v_mov_b32_e32 v94, v103
	s_waitcnt vmcnt(15)
	v_pk_fma_f32 v[10:11], v[178:179], v[60:61], v[10:11] op_sel_hi:[0,1,1]
	v_pk_fma_f32 v[8:9], v[178:179], v[76:77], v[8:9] op_sel_hi:[0,1,1]
	v_mov_b32_e32 v87, v80
	v_mov_b32_e32 v103, v96
	s_waitcnt vmcnt(14)
	v_pk_fma_f32 v[10:11], v[180:181], v[78:79], v[10:11] op_sel_hi:[0,1,1]
	v_pk_fma_f32 v[8:9], v[180:181], v[94:95], v[8:9] op_sel_hi:[0,1,1]
	v_mov_b32_e32 v80, v89
	v_mov_b32_e32 v96, v105
	s_waitcnt vmcnt(13)
	v_pk_fma_f32 v[10:11], v[182:183], v[86:87], v[10:11] op_sel_hi:[0,1,1]
	v_pk_fma_f32 v[8:9], v[182:183], v[102:103], v[8:9] op_sel_hi:[0,1,1]
	v_mov_b32_e32 v89, v82
	v_mov_b32_e32 v105, v98
	s_waitcnt vmcnt(12)
	v_pk_fma_f32 v[10:11], v[184:185], v[80:81], v[10:11] op_sel_hi:[0,1,1]
	v_pk_fma_f32 v[8:9], v[184:185], v[96:97], v[8:9] op_sel_hi:[0,1,1]
	v_mov_b32_e32 v82, v91
	v_mov_b32_e32 v98, v107
	s_waitcnt vmcnt(11)
	v_pk_fma_f32 v[10:11], v[186:187], v[88:89], v[10:11] op_sel_hi:[0,1,1]
	v_pk_fma_f32 v[8:9], v[186:187], v[104:105], v[8:9] op_sel_hi:[0,1,1]
	v_mov_b32_e32 v91, v84
	v_mov_b32_e32 v107, v100
	s_waitcnt vmcnt(10)
	v_pk_fma_f32 v[10:11], v[188:189], v[82:83], v[10:11] op_sel_hi:[0,1,1]
	v_pk_fma_f32 v[8:9], v[188:189], v[98:99], v[8:9] op_sel_hi:[0,1,1]
	v_mov_b32_e32 v84, v93
	v_mov_b32_e32 v100, v109
	s_waitcnt vmcnt(9)
	v_pk_fma_f32 v[10:11], v[192:193], v[90:91], v[10:11] op_sel_hi:[0,1,1]
	v_pk_fma_f32 v[8:9], v[192:193], v[106:107], v[8:9] op_sel_hi:[0,1,1]
	v_mov_b32_e32 v93, v110
	v_mov_b32_e32 v109, v126
	s_waitcnt vmcnt(8)
	v_pk_fma_f32 v[10:11], v[194:195], v[84:85], v[10:11] op_sel_hi:[0,1,1]
	v_pk_fma_f32 v[8:9], v[194:195], v[100:101], v[8:9] op_sel_hi:[0,1,1]
	v_mov_b32_e32 v110, v119
	v_mov_b32_e32 v126, v139
	s_waitcnt vmcnt(7)
	v_pk_fma_f32 v[10:11], v[196:197], v[92:93], v[10:11] op_sel_hi:[0,1,1]
	v_pk_fma_f32 v[8:9], v[196:197], v[108:109], v[8:9] op_sel_hi:[0,1,1]
	v_mov_b32_e32 v119, v112
	v_mov_b32_e32 v210, v140
	v_mov_b32_e32 v211, v128
	s_waitcnt vmcnt(6)
	v_pk_fma_f32 v[10:11], v[198:199], v[110:111], v[10:11] op_sel_hi:[0,1,1]
	v_pk_fma_f32 v[8:9], v[198:199], v[126:127], v[8:9] op_sel_hi:[0,1,1]
	v_mov_b32_e32 v112, v121
	v_mov_b32_e32 v128, v141
	s_waitcnt vmcnt(5)
	v_pk_fma_f32 v[10:11], v[200:201], v[118:119], v[10:11] op_sel_hi:[0,1,1]
	v_pk_fma_f32 v[8:9], v[200:201], v[210:211], v[8:9] op_sel_hi:[0,1,1]
	v_mov_b32_e32 v140, v122
	v_mov_b32_e32 v141, v114
	s_waitcnt lgkmcnt(0)
	v_mov_b32_e32 v212, v142
	v_mov_b32_e32 v213, v130
	s_waitcnt vmcnt(4)
	v_pk_fma_f32 v[10:11], v[202:203], v[112:113], v[10:11] op_sel_hi:[0,1,1]
	v_pk_fma_f32 v[8:9], v[202:203], v[128:129], v[8:9] op_sel_hi:[0,1,1]
	v_mov_b32_e32 v114, v123
	v_mov_b32_e32 v130, v143
	s_waitcnt vmcnt(3)
	v_pk_fma_f32 v[10:11], v[204:205], v[140:141], v[10:11] op_sel_hi:[0,1,1]
	v_pk_fma_f32 v[8:9], v[204:205], v[212:213], v[8:9] op_sel_hi:[0,1,1]
	v_mov_b32_e32 v122, v124
	v_mov_b32_e32 v123, v116
	v_mov_b32_e32 v142, v144
	v_mov_b32_e32 v143, v132
	s_waitcnt vmcnt(2)
	v_pk_fma_f32 v[10:11], v[206:207], v[114:115], v[10:11] op_sel_hi:[0,1,1]
	v_pk_fma_f32 v[8:9], v[206:207], v[130:131], v[8:9] op_sel_hi:[0,1,1]
	s_addk_i32 s42, 0x80
	v_mov_b32_e32 v116, v125
	v_mov_b32_e32 v132, v145
	s_waitcnt vmcnt(1)
	v_pk_fma_f32 v[10:11], v[208:209], v[122:123], v[10:11] op_sel_hi:[0,1,1]
	v_pk_fma_f32 v[8:9], v[208:209], v[142:143], v[8:9] op_sel_hi:[0,1,1]
	v_lshl_add_u64 v[6:7], v[6:7], 0, s[36:37]
	s_cmpk_eq_i32 s42, 0x200
	s_waitcnt vmcnt(0)
	v_pk_fma_f32 v[10:11], v[52:53], v[116:117], v[10:11] op_sel_hi:[0,1,1]
	v_pk_fma_f32 v[8:9], v[52:53], v[132:133], v[8:9] op_sel_hi:[0,1,1]
	s_cbranch_scc0 .LBB0_186
	ds_write2st64_b32 v5, v11, v10 offset0:64 offset1:65
	ds_write2st64_b32 v5, v9, v8 offset0:66 offset1:67
	s_waitcnt lgkmcnt(0)
	s_barrier
	s_and_saveexec_b64 s[36:37], s[4:5]
	s_cbranch_execz .LBB0_176
	v_add_u32_e32 v6, s26, v136
	v_ashrrev_i32_e32 v7, 31, v6
	v_lshl_add_u64 v[6:7], v[6:7], 2, s[28:29]
	global_load_dword v12, v[6:7], off nt
	ds_read2st64_b32 v[6:7], v13 offset0:64 offset1:68
	ds_read2st64_b32 v[8:9], v13 offset0:72 offset1:76
	ds_read2st64_b32 v[10:11], v13 offset0:80 offset1:84
	ds_read2st64_b32 v[14:15], v13 offset0:88 offset1:92
	v_mul_lo_u32 v18, s31, v4
	s_waitcnt lgkmcnt(3)
	v_add_f32_e32 v6, 0, v6
	v_add_f32_e32 v6, v6, v7
	s_waitcnt lgkmcnt(2)
	v_add_f32_e32 v6, v6, v8
	v_add_f32_e32 v6, v6, v9
	v_mul_lo_u32 v19, s30, v1
	v_mad_u64_u32 v[16:17], s[28:29], s30, v4, 0
	s_waitcnt lgkmcnt(1)
	v_add_f32_e32 v6, v6, v10
	v_add3_u32 v17, v17, v19, v18
	v_add_f32_e32 v6, v6, v11
	v_lshl_add_u64 v[16:17], v[16:17], 2, s[34:35]
	s_waitcnt lgkmcnt(0)
	v_add_f32_e32 v6, v6, v14
	v_lshl_add_u64 v[16:17], s[26:27], 2, v[16:17]
	v_add_f32_e32 v6, v6, v15
	s_waitcnt vmcnt(0)
	v_add_f32_e32 v8, v6, v12
	v_lshl_add_u64 v[6:7], v[16:17], 0, v[2:3]
	global_store_dword v[6:7], v8, off
	s_branch .LBB0_176
.LBB0_189:
	s_lshl_b32 s4, s3, 4
	s_abs_i32 s5, s4
	v_cvt_f32_u32_e32 v1, s5
	s_sub_i32 s6, 0, s5
	s_ashr_i32 s4, s4, 31
	s_mov_b32 s13, 0
	v_rcp_iflag_f32_e32 v1, v1
	s_nop 0
	v_mul_f32_e32 v1, 0x4f7ffffe, v1
	v_cvt_u32_f32_e32 v1, v1
	s_nop 0
	v_readfirstlane_b32 s7, v1
	s_mul_i32 s6, s6, s7
	s_mul_hi_u32 s6, s7, s6
	s_add_i32 s7, s7, s6
	s_lshr_b32 s6, s7, 17
	s_mul_i32 s7, s6, s5
	s_sub_i32 s7, 0x8000, s7
	s_add_i32 s8, s6, 1
	s_sub_i32 s9, s7, s5
	s_cmp_ge_u32 s7, s5
	s_cselect_b32 s6, s8, s6
	s_cselect_b32 s7, s9, s7
	s_add_i32 s8, s6, 1
	s_cmp_ge_u32 s7, s5
	s_cselect_b32 s5, s8, s6
	s_xor_b32 s5, s5, s4
	s_sub_i32 s12, s5, s4
	s_cmp_lt_i32 s12, 1
	s_cbranch_scc1 .LBB0_192
	v_and_b32_e32 v8, 31, v134
	v_lshlrev_b32_e32 v9, 2, v8
	global_load_dword v1, v9, s[0:1] offset:192 nt
	s_load_dwordx2 s[8:9], s[0:1], 0x10
	v_ashrrev_i32_e32 v2, 5, v134
	v_lshl_add_u32 v2, s2, 4, v2
	v_mul_lo_u32 v2, s12, v2
	v_ashrrev_i32_e32 v3, 31, v2
	s_add_u32 s4, s46, 0x200000
	v_lshlrev_b64 v[6:7], 7, v[2:3]
	s_addc_u32 s5, s47, 0
	v_or_b32_e32 v6, v6, v9
	s_mov_b64 s[10:11], 0x600000
	s_add_u32 s6, s46, 0x600000
	s_waitcnt lgkmcnt(0)
	v_lshl_add_u64 v[4:5], v[2:3], 2, s[8:9]
	v_lshl_add_u64 v[6:7], s[46:47], 0, v[6:7]
	s_mov_b32 s8, 0x6dc9c883
	s_addc_u32 s7, s47, 0
	v_lshl_add_u64 v[4:5], v[4:5], 0, 28
	v_lshl_add_u64 v[6:7], v[6:7], 0, s[10:11]
	s_mov_b32 s9, 0x3fc45f30
	s_mov_b32 s14, 0xffc00000
	v_lshlrev_b32_e32 v3, 2, v8
	s_mov_b64 s[10:11], 0x400
.LBB0_191:
	global_load_dwordx4 v[8:11], v[4:5], off offset:-28 nt
	global_load_dwordx4 v[12:15], v[4:5], off offset:-12 nt
	v_add_u32_e32 v19, s13, v2
	v_add_u32_e32 v18, 1, v19
	v_add_u32_e32 v20, 2, v19
	v_add_u32_e32 v22, 3, v19
	v_add_u32_e32 v24, 4, v19
	v_add_u32_e32 v26, 5, v19
	v_add_u32_e32 v28, 6, v19
	v_add_u32_e32 v30, 7, v19
	v_ashrrev_i32_e32 v19, 31, v18
	v_ashrrev_i32_e32 v21, 31, v20
	v_ashrrev_i32_e32 v23, 31, v22
	v_ashrrev_i32_e32 v25, 31, v24
	v_ashrrev_i32_e32 v27, 31, v26
	v_ashrrev_i32_e32 v29, 31, v28
	v_ashrrev_i32_e32 v31, 31, v30
	v_add_co_u32_e32 v16, vcc, s14, v6
	v_lshlrev_b64 v[18:19], 7, v[18:19]
	v_lshlrev_b64 v[20:21], 7, v[20:21]
	v_lshlrev_b64 v[22:23], 7, v[22:23]
	v_lshlrev_b64 v[24:25], 7, v[24:25]
	v_lshlrev_b64 v[26:27], 7, v[26:27]
	v_lshlrev_b64 v[28:29], 7, v[28:29]
	v_lshlrev_b64 v[30:31], 7, v[30:31]
	v_addc_co_u32_e32 v17, vcc, -1, v7, vcc
	s_add_i32 s13, s13, 8
	v_or_b32_e32 v18, v18, v3
	v_or_b32_e32 v20, v20, v3
	v_or_b32_e32 v22, v22, v3
	v_or_b32_e32 v24, v24, v3
	v_or_b32_e32 v26, v26, v3
	v_or_b32_e32 v28, v28, v3
	v_or_b32_e32 v30, v30, v3
	v_lshl_add_u64 v[4:5], v[4:5], 0, 32
	s_cmp_lt_i32 s13, s12
	v_lshl_add_u64 v[32:33], s[4:5], 0, v[18:19]
	v_lshl_add_u64 v[18:19], s[6:7], 0, v[18:19]
	v_lshl_add_u64 v[34:35], s[4:5], 0, v[20:21]
	v_lshl_add_u64 v[20:21], s[6:7], 0, v[20:21]
	v_lshl_add_u64 v[36:37], s[4:5], 0, v[22:23]
	v_lshl_add_u64 v[22:23], s[6:7], 0, v[22:23]
	v_lshl_add_u64 v[38:39], s[4:5], 0, v[24:25]
	v_lshl_add_u64 v[24:25], s[6:7], 0, v[24:25]
	v_lshl_add_u64 v[40:41], s[4:5], 0, v[26:27]
	v_lshl_add_u64 v[26:27], s[6:7], 0, v[26:27]
	v_lshl_add_u64 v[42:43], s[4:5], 0, v[28:29]
	v_lshl_add_u64 v[28:29], s[6:7], 0, v[28:29]
	v_lshl_add_u64 v[44:45], s[4:5], 0, v[30:31]
	v_lshl_add_u64 v[30:31], s[6:7], 0, v[30:31]
	s_waitcnt vmcnt(1)
	v_cvt_f32_i32_e32 v8, v8
	v_cvt_f32_i32_e32 v9, v9
	v_cvt_f32_i32_e32 v10, v10
	s_waitcnt vmcnt(0)
	v_cvt_f32_i32_e32 v12, v12
	v_cvt_f32_i32_e32 v11, v11
	v_cvt_f32_i32_e32 v13, v13
	v_cvt_f32_i32_e32 v14, v14
	v_cvt_f32_i32_e32 v15, v15
	v_mul_f32_e32 v8, v1, v8
	v_mul_f32_e32 v46, v1, v9
	v_mul_f32_e32 v47, v1, v10
	v_mul_f32_e32 v49, v1, v12
	v_cvt_f64_f32_e32 v[8:9], v8
	v_mul_f32_e32 v48, v1, v11
	v_mul_f32_e32 v50, v1, v13
	v_cvt_f64_f32_e32 v[10:11], v46
	v_cvt_f64_f32_e32 v[12:13], v47
	v_cvt_f64_f32_e32 v[46:47], v49
	v_mul_f64 v[8:9], v[8:9], s[8:9]
	v_mul_f64 v[10:11], v[10:11], s[8:9]
	v_mul_f64 v[12:13], v[12:13], s[8:9]
	v_mul_f64 v[46:47], v[46:47], s[8:9]
	v_fract_f64_e32 v[8:9], v[8:9]
	v_mul_f32_e32 v51, v1, v14
	v_mul_f32_e32 v52, v1, v15
	v_fract_f64_e32 v[10:11], v[10:11]
	v_fract_f64_e32 v[12:13], v[12:13]
	v_fract_f64_e32 v[46:47], v[46:47]
	v_cvt_f32_f64_e32 v8, v[8:9]
	v_cvt_f64_f32_e32 v[14:15], v48
	v_cvt_f64_f32_e32 v[48:49], v50
	v_cvt_f64_f32_e32 v[50:51], v51
	v_cvt_f64_f32_e32 v[52:53], v52
	v_cvt_f32_f64_e32 v9, v[10:11]
	v_cvt_f32_f64_e32 v10, v[12:13]
	v_cvt_f32_f64_e32 v12, v[46:47]
	v_cos_f32_e32 v46, v8
	v_mul_f64 v[14:15], v[14:15], s[8:9]
	v_mul_f64 v[48:49], v[48:49], s[8:9]
	v_mul_f64 v[50:51], v[50:51], s[8:9]
	v_mul_f64 v[52:53], v[52:53], s[8:9]
	v_sin_f32_e32 v8, v8
	v_fract_f64_e32 v[14:15], v[14:15]
	v_fract_f64_e32 v[48:49], v[48:49]
	v_fract_f64_e32 v[50:51], v[50:51]
	v_fract_f64_e32 v[52:53], v[52:53]
	v_cos_f32_e32 v47, v9
	v_cvt_f32_f64_e32 v11, v[14:15]
	v_cvt_f32_f64_e32 v13, v[48:49]
	v_cvt_f32_f64_e32 v14, v[50:51]
	v_cvt_f32_f64_e32 v15, v[52:53]
	v_sin_f32_e32 v9, v9
	v_cos_f32_e32 v48, v10
	v_sin_f32_e32 v10, v10
	v_cos_f32_e32 v49, v11
	v_sin_f32_e32 v11, v11
	v_cos_f32_e32 v50, v12
	v_sin_f32_e32 v12, v12
	v_cos_f32_e32 v51, v13
	v_sin_f32_e32 v13, v13
	v_cos_f32_e32 v52, v14
	v_sin_f32_e32 v14, v14
	v_cos_f32_e32 v53, v15
	v_sin_f32_e32 v15, v15
	global_store_dword v[16:17], v46, off
	global_store_dword v[6:7], v8, off
	global_store_dword v[32:33], v47, off
	global_store_dword v[18:19], v9, off
	global_store_dword v[34:35], v48, off
	global_store_dword v[20:21], v10, off
	global_store_dword v[36:37], v49, off
	global_store_dword v[22:23], v11, off
	global_store_dword v[38:39], v50, off
	global_store_dword v[24:25], v12, off
	global_store_dword v[40:41], v51, off
	global_store_dword v[26:27], v13, off
	global_store_dword v[42:43], v52, off
	global_store_dword v[28:29], v14, off
	global_store_dword v[44:45], v53, off
	global_store_dword v[30:31], v15, off
	v_lshl_add_u64 v[6:7], v[6:7], 0, s[10:11]
	s_cbranch_scc1 .LBB0_191

.LBB0_438:
	s_waitcnt vmcnt(0)
	v_lshl_add_u64 v[16:17], s[46:47], 0, v[6:7]
	v_add_co_u32_e32 v12, vcc, 0xc000000, v16
	v_lshl_add_u64 v[10:11], s[46:47], 0, v[2:3]
	s_nop 0
	v_addc_co_u32_e32 v13, vcc, 0, v17, vcc
	v_add_co_u32_e32 v14, vcc, 0xf00000, v10
	v_mov_b32_e32 v62, 0
	s_nop 0
	v_addc_co_u32_e32 v15, vcc, 0, v11, vcc
	v_add_co_u32_e32 v18, vcc, 0xf02000, v10
	v_mov_b32_e32 v80, 0
	s_nop 0
	v_addc_co_u32_e32 v19, vcc, 0, v11, vcc
	global_load_dwordx2 v[78:79], v[12:13], off nt
	global_load_dword v115, v[14:15], off nt
	global_load_dword v111, v[18:19], off nt
	v_mov_b32_e32 v81, 0
	s_and_saveexec_b64 s[20:21], s[4:5]
	s_cbranch_execz .LBB0_440
	v_lshl_add_u64 v[12:13], s[46:47], 0, v[4:5]
	v_add_co_u32_e32 v12, vcc, 0x6000000, v12
	s_nop 1
	v_addc_co_u32_e32 v13, vcc, 0, v13, vcc
	global_load_dwordx2 v[80:81], v[12:13], off nt
.LBB0_440:
	s_or_b64 exec, exec, s[20:21]
	v_add_co_u32_e32 v12, vcc, 0xc008000, v16
	v_mov_b32_e32 v63, 0
	s_nop 0
	v_addc_co_u32_e32 v13, vcc, 0, v17, vcc
	v_add_co_u32_e32 v14, vcc, 0xf00000, v10
	s_nop 1
	v_addc_co_u32_e32 v15, vcc, 0, v11, vcc
	v_add_co_u32_e32 v18, vcc, 0xf02000, v10
	s_nop 1
	v_addc_co_u32_e32 v19, vcc, 0, v11, vcc
	global_load_dwordx2 v[74:75], v[12:13], off nt
	global_load_dword v114, v[14:15], off offset:4 nt
	global_load_dword v109, v[18:19], off offset:4 nt
	s_and_saveexec_b64 s[20:21], s[4:5]
	s_cbranch_execz .LBB0_442
	v_lshl_add_u64 v[12:13], s[46:47], 0, v[4:5]
	v_add_co_u32_e32 v12, vcc, 0x6000000, v12
	s_nop 1
	v_addc_co_u32_e32 v13, vcc, 0, v13, vcc
	global_load_dwordx2 v[62:63], v[12:13], off offset:256 nt
.LBB0_442:
	s_or_b64 exec, exec, s[20:21]
	v_add_co_u32_e32 v12, vcc, 0xc010000, v16
	v_mov_b32_e32 v48, 0
	s_nop 0
	v_addc_co_u32_e32 v13, vcc, 0, v17, vcc
	v_add_co_u32_e32 v14, vcc, 0xf00000, v10
	v_mov_b32_e32 v76, 0
	s_nop 0
	v_addc_co_u32_e32 v15, vcc, 0, v11, vcc
	v_add_co_u32_e32 v18, vcc, 0xf02000, v10
	v_mov_b32_e32 v77, 0
	s_nop 0
	v_addc_co_u32_e32 v19, vcc, 0, v11, vcc
	global_load_dwordx2 v[72:73], v[12:13], off nt
	global_load_dword v113, v[14:15], off offset:8 nt
	global_load_dword v107, v[18:19], off offset:8 nt
	s_and_saveexec_b64 s[20:21], s[4:5]
	s_cbranch_execz .LBB0_444
	v_lshl_add_u64 v[12:13], s[46:47], 0, v[4:5]
	v_add_co_u32_e32 v12, vcc, 0x6000000, v12
	s_nop 1
	v_addc_co_u32_e32 v13, vcc, 0, v13, vcc
	global_load_dwordx2 v[76:77], v[12:13], off offset:512 nt
.LBB0_444:
	s_or_b64 exec, exec, s[20:21]
	v_add_co_u32_e32 v12, vcc, 0xc018000, v16
	v_mov_b32_e32 v49, 0
	s_nop 0
	v_addc_co_u32_e32 v13, vcc, 0, v17, vcc
	v_add_co_u32_e32 v14, vcc, 0xf00000, v10
	s_nop 1
	v_addc_co_u32_e32 v15, vcc, 0, v11, vcc
	v_add_co_u32_e32 v18, vcc, 0xf02000, v10
	s_nop 1
	v_addc_co_u32_e32 v19, vcc, 0, v11, vcc
	global_load_dwordx2 v[68:69], v[12:13], off nt
	global_load_dword v112, v[14:15], off offset:12 nt
	global_load_dword v104, v[18:19], off offset:12 nt
	s_and_saveexec_b64 s[20:21], s[4:5]
	s_cbranch_execz .LBB0_446
	v_lshl_add_u64 v[12:13], s[46:47], 0, v[4:5]
	v_add_co_u32_e32 v12, vcc, 0x6000000, v12
	s_nop 1
	v_addc_co_u32_e32 v13, vcc, 0, v13, vcc
	global_load_dwordx2 v[48:49], v[12:13], off offset:768 nt
.LBB0_446:
	s_or_b64 exec, exec, s[20:21]
	v_add_co_u32_e32 v12, vcc, 0xc020000, v16
	v_mov_b32_e32 v40, 0
	s_nop 0
	v_addc_co_u32_e32 v13, vcc, 0, v17, vcc
	v_add_co_u32_e32 v14, vcc, 0xf00000, v10
	v_mov_b32_e32 v70, 0
	s_nop 0
	v_addc_co_u32_e32 v15, vcc, 0, v11, vcc
	v_add_co_u32_e32 v18, vcc, 0xf02000, v10
	v_mov_b32_e32 v71, 0
	s_nop 0
	v_addc_co_u32_e32 v19, vcc, 0, v11, vcc
	global_load_dwordx2 v[66:67], v[12:13], off nt
	global_load_dword v110, v[14:15], off offset:16 nt
	global_load_dword v102, v[18:19], off offset:16 nt
	s_and_saveexec_b64 s[20:21], s[4:5]
	s_cbranch_execz .LBB0_448
	v_lshl_add_u64 v[12:13], s[46:47], 0, v[4:5]
	v_add_co_u32_e32 v12, vcc, 0x6000000, v12
	s_nop 1
	v_addc_co_u32_e32 v13, vcc, 0, v13, vcc
	global_load_dwordx2 v[70:71], v[12:13], off offset:1024 nt
.LBB0_448:
	s_or_b64 exec, exec, s[20:21]
	v_add_co_u32_e32 v12, vcc, 0xc028000, v16
	v_mov_b32_e32 v41, 0
	s_nop 0
	v_addc_co_u32_e32 v13, vcc, 0, v17, vcc
	v_add_co_u32_e32 v14, vcc, 0xf00000, v10
	s_nop 1
	v_addc_co_u32_e32 v15, vcc, 0, v11, vcc
	v_add_co_u32_e32 v18, vcc, 0xf02000, v10
	s_nop 1
	v_addc_co_u32_e32 v19, vcc, 0, v11, vcc
	global_load_dwordx2 v[60:61], v[12:13], off nt
	global_load_dword v108, v[14:15], off offset:20 nt
	global_load_dword v100, v[18:19], off offset:20 nt
	s_and_saveexec_b64 s[20:21], s[4:5]
	s_cbranch_execz .LBB0_450
	v_lshl_add_u64 v[12:13], s[46:47], 0, v[4:5]
	v_add_co_u32_e32 v12, vcc, 0x6000000, v12
	s_nop 1
	v_addc_co_u32_e32 v13, vcc, 0, v13, vcc
	global_load_dwordx2 v[40:41], v[12:13], off offset:1280 nt
.LBB0_450:
	s_or_b64 exec, exec, s[20:21]
	v_add_co_u32_e32 v12, vcc, 0xc030000, v16
	v_mov_b32_e32 v32, 0
	s_nop 0
	v_addc_co_u32_e32 v13, vcc, 0, v17, vcc
	v_add_co_u32_e32 v14, vcc, 0xf00000, v10
	v_mov_b32_e32 v64, 0
	s_nop 0
	v_addc_co_u32_e32 v15, vcc, 0, v11, vcc
	v_add_co_u32_e32 v18, vcc, 0xf02000, v10
	v_mov_b32_e32 v65, 0
	s_nop 0
	v_addc_co_u32_e32 v19, vcc, 0, v11, vcc
	global_load_dwordx2 v[56:57], v[12:13], off nt
	global_load_dword v105, v[14:15], off offset:24 nt
	global_load_dword v98, v[18:19], off offset:24 nt
	s_and_saveexec_b64 s[20:21], s[4:5]
	s_cbranch_execz .LBB0_452
	v_lshl_add_u64 v[12:13], s[46:47], 0, v[4:5]
	v_add_co_u32_e32 v12, vcc, 0x6000000, v12
	s_nop 1
	v_addc_co_u32_e32 v13, vcc, 0, v13, vcc
	global_load_dwordx2 v[64:65], v[12:13], off offset:1536 nt
.LBB0_452:
	s_or_b64 exec, exec, s[20:21]
	v_add_co_u32_e32 v12, vcc, 0xc038000, v16
	v_mov_b32_e32 v33, 0
	s_nop 0
	v_addc_co_u32_e32 v13, vcc, 0, v17, vcc
	v_add_co_u32_e32 v14, vcc, 0xf00000, v10
	s_nop 1
	v_addc_co_u32_e32 v15, vcc, 0, v11, vcc
	v_add_co_u32_e32 v18, vcc, 0xf02000, v10
	s_nop 1
	v_addc_co_u32_e32 v19, vcc, 0, v11, vcc
	global_load_dwordx2 v[46:47], v[12:13], off nt
	global_load_dword v103, v[14:15], off offset:28 nt
	global_load_dword v96, v[18:19], off offset:28 nt
	s_and_saveexec_b64 s[20:21], s[4:5]
	s_cbranch_execz .LBB0_454
	v_lshl_add_u64 v[12:13], s[46:47], 0, v[4:5]
	v_add_co_u32_e32 v12, vcc, 0x6000000, v12
	s_nop 1
	v_addc_co_u32_e32 v13, vcc, 0, v13, vcc
	global_load_dwordx2 v[32:33], v[12:13], off offset:1792 nt
.LBB0_454:
	s_or_b64 exec, exec, s[20:21]
	v_add_co_u32_e32 v12, vcc, 0xc040000, v16
	v_mov_b32_e32 v24, 0
	s_nop 0
	v_addc_co_u32_e32 v13, vcc, 0, v17, vcc
	v_add_co_u32_e32 v14, vcc, 0xf00000, v10
	v_mov_b32_e32 v50, 0
	s_nop 0
	v_addc_co_u32_e32 v15, vcc, 0, v11, vcc
	v_add_co_u32_e32 v18, vcc, 0xf02000, v10
	v_mov_b32_e32 v51, 0
	s_nop 0
	v_addc_co_u32_e32 v19, vcc, 0, v11, vcc
	global_load_dwordx2 v[44:45], v[12:13], off nt
	global_load_dword v101, v[14:15], off offset:32 nt
	global_load_dword v94, v[18:19], off offset:32 nt
	s_and_saveexec_b64 s[20:21], s[4:5]
	s_cbranch_execz .LBB0_456
	v_lshl_add_u64 v[12:13], s[46:47], 0, v[4:5]
	v_add_co_u32_e32 v12, vcc, 0x6000000, v12
	s_nop 1
	v_addc_co_u32_e32 v13, vcc, 0, v13, vcc
	global_load_dwordx2 v[50:51], v[12:13], off offset:2048 nt
.LBB0_456:
	s_or_b64 exec, exec, s[20:21]
	v_add_co_u32_e32 v12, vcc, 0xc048000, v16
	v_mov_b32_e32 v25, 0
	s_nop 0
	v_addc_co_u32_e32 v13, vcc, 0, v17, vcc
	v_add_co_u32_e32 v14, vcc, 0xf00000, v10
	s_nop 1
	v_addc_co_u32_e32 v15, vcc, 0, v11, vcc
	v_add_co_u32_e32 v18, vcc, 0xf02000, v10
	s_nop 1
	v_addc_co_u32_e32 v19, vcc, 0, v11, vcc
	global_load_dwordx2 v[38:39], v[12:13], off nt
	global_load_dword v99, v[14:15], off offset:36 nt
	global_load_dword v92, v[18:19], off offset:36 nt
	s_and_saveexec_b64 s[20:21], s[4:5]
	s_cbranch_execz .LBB0_458
	v_lshl_add_u64 v[12:13], s[46:47], 0, v[4:5]
	v_add_co_u32_e32 v12, vcc, 0x6000000, v12
	s_nop 1
	v_addc_co_u32_e32 v13, vcc, 0, v13, vcc
	global_load_dwordx2 v[24:25], v[12:13], off offset:2304 nt
.LBB0_458:
	s_or_b64 exec, exec, s[20:21]
	v_add_co_u32_e32 v12, vcc, 0xc050000, v16
	v_mov_b32_e32 v42, 0
	s_nop 0
	v_addc_co_u32_e32 v13, vcc, 0, v17, vcc
	v_add_co_u32_e32 v14, vcc, 0xf00000, v10
	v_mov_b32_e32 v43, 0
	s_nop 0
	v_addc_co_u32_e32 v15, vcc, 0, v11, vcc
	v_add_co_u32_e32 v18, vcc, 0xf02000, v10
	s_nop 1
	v_addc_co_u32_e32 v19, vcc, 0, v11, vcc
	global_load_dwordx2 v[36:37], v[12:13], off nt
	global_load_dword v97, v[14:15], off offset:40 nt
	global_load_dword v90, v[18:19], off offset:40 nt
	v_mov_b32_e32 v18, 0
	s_and_saveexec_b64 s[20:21], s[4:5]
	s_cbranch_execz .LBB0_460
	v_lshl_add_u64 v[12:13], s[46:47], 0, v[4:5]
	v_add_co_u32_e32 v12, vcc, 0x6000000, v12
	s_nop 1
	v_addc_co_u32_e32 v13, vcc, 0, v13, vcc
	global_load_dwordx2 v[42:43], v[12:13], off offset:2560 nt
.LBB0_460:
	s_or_b64 exec, exec, s[20:21]
	v_add_co_u32_e32 v12, vcc, 0xc058000, v16
	v_mov_b32_e32 v19, 0
	s_nop 0
	v_addc_co_u32_e32 v13, vcc, 0, v17, vcc
	v_add_co_u32_e32 v14, vcc, 0xf00000, v10
	s_nop 1
	v_addc_co_u32_e32 v15, vcc, 0, v11, vcc
	v_add_co_u32_e32 v20, vcc, 0xf02000, v10
	s_nop 1
	v_addc_co_u32_e32 v21, vcc, 0, v11, vcc
	global_load_dwordx2 v[30:31], v[12:13], off nt
	global_load_dword v95, v[14:15], off offset:44 nt
	global_load_dword v88, v[20:21], off offset:44 nt
	s_and_saveexec_b64 s[20:21], s[4:5]
	s_cbranch_execz .LBB0_462
	v_lshl_add_u64 v[12:13], s[46:47], 0, v[4:5]
	v_add_co_u32_e32 v12, vcc, 0x6000000, v12
	s_nop 1
	v_addc_co_u32_e32 v13, vcc, 0, v13, vcc
	global_load_dwordx2 v[18:19], v[12:13], off offset:2816 nt
.LBB0_462:
	s_or_b64 exec, exec, s[20:21]
	v_add_co_u32_e32 v12, vcc, 0xc060000, v16
	v_mov_b32_e32 v34, 0
	s_nop 0
	v_addc_co_u32_e32 v13, vcc, 0, v17, vcc
	v_add_co_u32_e32 v14, vcc, 0xf00000, v10
	v_mov_b32_e32 v35, 0
	s_nop 0
	v_addc_co_u32_e32 v15, vcc, 0, v11, vcc
	v_add_co_u32_e32 v20, vcc, 0xf02000, v10
	s_nop 1
	v_addc_co_u32_e32 v21, vcc, 0, v11, vcc
	global_load_dwordx2 v[28:29], v[12:13], off nt
	global_load_dword v93, v[14:15], off offset:48 nt
	global_load_dword v86, v[20:21], off offset:48 nt
	v_mov_b32_e32 v14, 0
	s_and_saveexec_b64 s[20:21], s[4:5]
	s_cbranch_execz .LBB0_464
	v_lshl_add_u64 v[12:13], s[46:47], 0, v[4:5]
	v_add_co_u32_e32 v12, vcc, 0x6000000, v12
	s_nop 1
	v_addc_co_u32_e32 v13, vcc, 0, v13, vcc
	global_load_dwordx2 v[34:35], v[12:13], off offset:3072 nt
.LBB0_464:
	s_or_b64 exec, exec, s[20:21]
	v_add_co_u32_e32 v12, vcc, 0xc068000, v16
	v_mov_b32_e32 v15, 0
	s_nop 0
	v_addc_co_u32_e32 v13, vcc, 0, v17, vcc
	v_add_co_u32_e32 v20, vcc, 0xf00000, v10
	s_nop 1
	v_addc_co_u32_e32 v21, vcc, 0, v11, vcc
	v_add_co_u32_e32 v26, vcc, 0xf02000, v10
	s_nop 1
	v_addc_co_u32_e32 v27, vcc, 0, v11, vcc
	global_load_dwordx2 v[22:23], v[12:13], off nt
	global_load_dword v91, v[20:21], off offset:52 nt
	global_load_dword v84, v[26:27], off offset:52 nt
	s_and_saveexec_b64 s[20:21], s[4:5]
	s_cbranch_execz .LBB0_466
	v_lshl_add_u64 v[12:13], s[46:47], 0, v[4:5]
	v_add_co_u32_e32 v12, vcc, 0x6000000, v12
	s_nop 1
	v_addc_co_u32_e32 v13, vcc, 0, v13, vcc
	global_load_dwordx2 v[14:15], v[12:13], off offset:3328 nt
.LBB0_466:
	s_or_b64 exec, exec, s[20:21]
	v_add_co_u32_e32 v12, vcc, 0xc070000, v16
	s_nop 1
	v_addc_co_u32_e32 v13, vcc, 0, v17, vcc
	v_add_co_u32_e32 v26, vcc, 0xf00000, v10
	s_nop 1
	v_addc_co_u32_e32 v27, vcc, 0, v11, vcc
	v_add_co_u32_e32 v58, vcc, 0xf02000, v10
	s_nop 1
	v_addc_co_u32_e32 v59, vcc, 0, v11, vcc
	global_load_dwordx2 v[20:21], v[12:13], off nt
	global_load_dword v89, v[26:27], off offset:56 nt
	global_load_dword v0, v[58:59], off offset:56 nt
	v_mov_b32_e32 v12, 0
	v_mov_b32_e32 v26, 0
	v_mov_b32_e32 v27, 0
	s_and_saveexec_b64 s[20:21], s[4:5]
	s_cbranch_execz .LBB0_468
	v_lshl_add_u64 v[26:27], s[46:47], 0, v[4:5]
	v_add_co_u32_e32 v26, vcc, 0x6000000, v26
	s_nop 1
	v_addc_co_u32_e32 v27, vcc, 0, v27, vcc
	global_load_dwordx2 v[26:27], v[26:27], off offset:3584 nt
.LBB0_468:
	s_or_b64 exec, exec, s[20:21]
	v_add_co_u32_e32 v58, vcc, 0xc078000, v16
	v_mov_b32_e32 v13, 0
	s_nop 0
	v_addc_co_u32_e32 v59, vcc, 0, v17, vcc
	v_add_co_u32_e32 v116, vcc, 0xf00000, v10
	s_nop 1
	v_addc_co_u32_e32 v117, vcc, 0, v11, vcc
	v_add_co_u32_e32 v118, vcc, 0xf02000, v10
	s_nop 1
	v_addc_co_u32_e32 v119, vcc, 0, v11, vcc
	global_load_dwordx2 v[16:17], v[58:59], off nt
	global_load_dword v87, v[116:117], off offset:60 nt
	global_load_dword v85, v[118:119], off offset:60 nt
	s_and_saveexec_b64 s[20:21], s[4:5]
	s_cbranch_execz .LBB0_470
	v_lshl_add_u64 v[12:13], s[46:47], 0, v[4:5]
	v_add_co_u32_e32 v12, vcc, 0x6000000, v12
	s_nop 1
	v_addc_co_u32_e32 v13, vcc, 0, v13, vcc
	global_load_dwordx2 v[12:13], v[12:13], off offset:3840 nt

.LBB0_594:
	v_ashrrev_i32_e32 v7, 31, v1
	v_mov_b32_e32 v6, v1
	v_ashrrev_i32_e32 v9, 31, v0
	v_mov_b32_e32 v8, v0
	v_add_u32_e32 v10, 0x400, v0
	v_add_u32_e32 v12, 0x400, v1
	v_add_u32_e32 v14, 0x800, v0
	s_waitcnt vmcnt(0)
	v_add_u32_e32 v16, 0x800, v1
	v_add_u32_e32 v18, 0xc00, v0
	v_add_u32_e32 v20, 0xc00, v1
	v_add_u32_e32 v22, 0x1000, v0
	v_add_u32_e32 v24, 0x1000, v1
	v_add_u32_e32 v26, 0x1400, v0
	v_add_u32_e32 v28, 0x1400, v1
	v_add_u32_e32 v30, 0x1800, v0
	v_add_u32_e32 v32, 0x1800, v1
	v_add_u32_e32 v34, 0x1c00, v0
	v_add_u32_e32 v36, 0x1c00, v1
	s_waitcnt lgkmcnt(0)
	v_lshl_add_u64 v[8:9], v[8:9], 2, s[6:7]
	v_lshl_add_u64 v[6:7], v[6:7], 2, s[6:7]
	v_ashrrev_i32_e32 v13, 31, v12
	v_ashrrev_i32_e32 v11, 31, v10
	v_ashrrev_i32_e32 v17, 31, v16
	v_ashrrev_i32_e32 v15, 31, v14
	v_ashrrev_i32_e32 v21, 31, v20
	v_ashrrev_i32_e32 v19, 31, v18
	v_ashrrev_i32_e32 v25, 31, v24
	v_ashrrev_i32_e32 v23, 31, v22
	v_ashrrev_i32_e32 v29, 31, v28
	v_ashrrev_i32_e32 v27, 31, v26
	v_ashrrev_i32_e32 v33, 31, v32
	v_ashrrev_i32_e32 v31, 31, v30
	v_ashrrev_i32_e32 v37, 31, v36
	v_ashrrev_i32_e32 v35, 31, v34
	v_lshl_add_u64 v[10:11], v[10:11], 2, s[6:7]
	v_lshl_add_u64 v[12:13], v[12:13], 2, s[6:7]
	v_lshl_add_u64 v[14:15], v[14:15], 2, s[6:7]
	v_lshl_add_u64 v[16:17], v[16:17], 2, s[6:7]
	v_lshl_add_u64 v[18:19], v[18:19], 2, s[6:7]
	v_lshl_add_u64 v[20:21], v[20:21], 2, s[6:7]
	v_lshl_add_u64 v[22:23], v[22:23], 2, s[6:7]
	v_lshl_add_u64 v[24:25], v[24:25], 2, s[6:7]
	v_lshl_add_u64 v[26:27], v[26:27], 2, s[6:7]
	v_lshl_add_u64 v[28:29], v[28:29], 2, s[6:7]
	v_lshl_add_u64 v[30:31], v[30:31], 2, s[6:7]
	v_lshl_add_u64 v[32:33], v[32:33], 2, s[6:7]
	v_lshl_add_u64 v[34:35], v[34:35], 2, s[6:7]
	v_lshl_add_u64 v[36:37], v[36:37], 2, s[6:7]
	global_load_dword v38, v[8:9], off nt
	global_load_dword v39, v[6:7], off nt
	global_load_dword v40, v[10:11], off nt
	global_load_dword v41, v[12:13], off nt
	global_load_dword v42, v[14:15], off nt
	global_load_dword v43, v[16:17], off nt
	global_load_dword v44, v[18:19], off nt
	global_load_dword v45, v[20:21], off nt
	global_load_dword v46, v[22:23], off nt
	global_load_dword v47, v[24:25], off nt
	global_load_dword v48, v[26:27], off nt
	global_load_dword v49, v[28:29], off nt
	global_load_dword v50, v[30:31], off nt
	global_load_dword v51, v[32:33], off nt
	global_load_dword v52, v[34:35], off nt
	global_load_dword v7, v[36:37], off nt
	v_add_u32_e32 v4, -8, v4
	s_add_i32 s14, s14, 16
	v_cmp_eq_u32_e32 vcc, 0, v4
	v_add_u32_e32 v1, 0x2000, v1
	v_add_u32_e32 v0, 0x2000, v0
	v_mov_b32_e32 v6, s14
	s_or_b64 s[12:13], vcc, s[12:13]
	s_waitcnt vmcnt(14)
	ds_write2st64_b32 v5, v38, v39 offset1:8
	s_waitcnt vmcnt(12)
	ds_write2st64_b32 v5, v40, v41 offset0:16 offset1:24
	s_waitcnt vmcnt(10)
	ds_write2st64_b32 v5, v42, v43 offset0:32 offset1:40
	s_waitcnt vmcnt(8)
	ds_write2st64_b32 v5, v44, v45 offset0:48 offset1:56
	s_waitcnt vmcnt(6)
	ds_write2st64_b32 v5, v46, v47 offset0:64 offset1:72
	s_waitcnt vmcnt(4)
	ds_write2st64_b32 v5, v48, v49 offset0:80 offset1:88
	s_waitcnt vmcnt(2)
	ds_write2st64_b32 v5, v50, v51 offset0:96 offset1:104
	s_waitcnt vmcnt(0)
	ds_write2st64_b32 v5, v52, v7 offset0:112 offset1:120
	v_add_u32_e32 v5, 0x8000, v5
	s_andn2_b64 exec, exec, s[12:13]
	s_cbranch_execnz .LBB0_594
	s_or_b64 exec, exec, s[12:13]

.LBB0_598:
	v_ashrrev_i32_e32 v9, 31, v0
	v_mov_b32_e32 v8, v0
	v_ashrrev_i32_e32 v7, 31, v1
	v_mov_b32_e32 v6, v1
	s_waitcnt lgkmcnt(0)
	v_lshl_add_u64 v[8:9], v[8:9], 2, s[6:7]
	v_lshl_add_u64 v[6:7], v[6:7], 2, s[6:7]
	global_load_dword v5, v[8:9], off nt
	global_load_dword v10, v[6:7], off nt
	v_add_u32_e32 v3, -1, v3
	v_add_u32_e32 v6, 0xfffff800, v4
	v_cmp_eq_u32_e32 vcc, 0, v3
	v_add_u32_e32 v1, 0x400, v1
	v_add_u32_e32 v0, 0x400, v0
	s_or_b64 s[12:13], vcc, s[12:13]
	s_waitcnt vmcnt(0)
	ds_write_b32 v6, v5
	ds_write_b32 v4, v10
	v_add_u32_e32 v4, 0x1000, v4
	s_andn2_b64 exec, exec, s[12:13]
	s_cbranch_execnz .LBB0_598

.LBB0_602:
	global_load_dword v4, v[0:1], off nt
	v_add_u32_e32 v2, 0x200, v2
	v_cmp_lt_i32_e32 vcc, s10, v2
	v_lshl_add_u64 v[0:1], v[0:1], 0, s[8:9]
	s_or_b64 s[6:7], vcc, s[6:7]
	s_waitcnt vmcnt(0)
	ds_write_b32 v3, v4
	v_add_u32_e32 v3, 0x800, v3
	s_andn2_b64 exec, exec, s[6:7]
	s_cbranch_execnz .LBB0_602
.LBB0_603:
	s_or_b64 exec, exec, s[4:5]
	s_cmpk_lt_i32 s2, 0x800
	s_cbranch_scc0 .LBB0_628
	s_add_u32 s62, s46, 0x10000000
	s_addc_u32 s63, s47, 0
	s_add_u32 s8, s46, 0x18000000
	s_addc_u32 s9, s47, 0
	s_add_u32 s73, s46, 0xc00000
	s_addc_u32 s76, s47, 0
	s_add_u32 s12, s46, 0x4000000
	s_addc_u32 s13, s47, 0
	s_add_u32 s10, s46, 0x6100000
	s_addc_u32 s11, s47, 0
	s_lshl_b32 s4, s2, 6
	s_and_b32 s4, s4, 0x1c0
	s_and_b32 s5, s2, 0xfffffe00
	s_or_b32 s4, s4, s5
	s_bfe_u32 s5, s2, 0x60003
	s_waitcnt lgkmcnt(0)
	s_or_b32 s6, s4, s5
	s_ashr_i32 s14, s4, 6
	s_lshl_b32 s4, s2, 4
	s_and_b32 s4, s4, 0xffffe000
	s_lshl_b32 s20, s5, 7
	s_or_b32 s16, s20, s4
	v_ashrrev_i32_e32 v147, 3, v120
	v_add_u32_e32 v7, 0x200, v120
	s_ashr_i32 s7, s6, 31
	v_add_u32_e32 v2, s16, v147
	v_ashrrev_i32_e32 v149, 3, v7
	s_and_b32 s15, s14, 7
	s_lshl_b64 s[18:19], s[6:7], 14
	v_ashrrev_i32_e32 v3, 31, v2
	v_add_u32_e32 v4, s16, v149
	v_lshlrev_b32_e32 v6, 3, v120
	s_add_u32 s18, s12, s18
	v_lshlrev_b64 v[2:3], 12, v[2:3]
	v_ashrrev_i32_e32 v5, 31, v4
	v_and_b32_e32 v0, 56, v6
	s_mov_b32 s5, 0
	s_addc_u32 s19, s13, s19
	v_lshl_add_u64 v[2:3], s[62:63], 0, v[2:3]
	s_lshl_b32 s4, s15, 7
	v_lshlrev_b64 v[4:5], 12, v[4:5]
	v_mov_b32_e32 v123, 0
	v_lshlrev_b32_e32 v122, 1, v0
	v_lshl_add_u64 v[2:3], v[2:3], 0, s[4:5]
	v_lshlrev_b32_e32 v124, 6, v147
	v_lshl_add_u64 v[4:5], s[62:63], 0, v[4:5]
	v_lshlrev_b32_e32 v126, 6, v149
	v_lshl_add_u64 v[0:1], s[18:19], 0, v[122:123]
	v_lshl_add_u64 v[2:3], v[2:3], 0, v[122:123]
	v_ashrrev_i32_e32 v125, 31, v124
	v_lshl_add_u64 v[4:5], v[4:5], 0, s[4:5]
	v_ashrrev_i32_e32 v127, 31, v126
	s_ashr_i32 s17, s16, 31
	global_load_dwordx4 v[48:51], v[2:3], off nt
	global_load_dwordx4 v[52:55], v[2:3], off offset:1024 nt
	v_lshl_add_u64 v[2:3], v[124:125], 1, v[0:1]
	v_lshl_add_u64 v[4:5], v[4:5], 0, v[122:123]
	v_lshl_add_u64 v[0:1], v[126:127], 1, v[0:1]
	s_lshl_b64 s[18:19], s[16:17], 1
	v_ashrrev_i32_e32 v150, 4, v120
	v_ashrrev_i32_e32 v151, 4, v7
	global_load_dwordx4 v[56:59], v[2:3], off nt
	global_load_dwordx4 v[60:63], v[4:5], off nt
	global_load_dwordx4 v[64:67], v[4:5], off offset:1024 nt
	global_load_dwordx4 v[68:71], v[0:1], off nt
	s_add_u32 s18, s8, s18
	v_and_b32_e32 v0, 0x78, v6
	v_add_u32_e32 v2, s4, v150
	v_add_u32_e32 v4, s4, v151
	s_addc_u32 s19, s9, s19
	v_lshlrev_b32_e32 v128, 1, v0
	v_mov_b32_e32 v129, v123
	v_ashrrev_i32_e32 v3, 31, v2
	v_ashrrev_i32_e32 v5, 31, v4
	v_lshl_add_u64 v[0:1], s[18:19], 0, v[128:129]
	v_lshlrev_b64 v[2:3], 16, v[2:3]
	v_lshlrev_b64 v[4:5], 16, v[4:5]
	v_lshl_add_u64 v[2:3], v[0:1], 0, v[2:3]
	v_lshl_add_u64 v[4:5], v[0:1], 0, v[4:5]
	global_load_dwordx4 v[72:75], v[2:3], off nt
	global_load_dwordx4 v[76:79], v[4:5], off nt
	v_add_u32_e32 v2, 0x400, v120
	v_add_u32_e32 v4, 0x600, v120
	v_ashrrev_i32_e32 v152, 4, v2
	v_ashrrev_i32_e32 v153, 4, v4
	v_add_u32_e32 v2, s4, v152
	v_add_u32_e32 v4, s4, v153
	v_ashrrev_i32_e32 v3, 31, v2
	v_ashrrev_i32_e32 v5, 31, v4
	v_lshlrev_b64 v[2:3], 16, v[2:3]
	v_lshlrev_b64 v[4:5], 16, v[4:5]
	v_lshl_add_u64 v[2:3], v[0:1], 0, v[2:3]
	v_lshl_add_u64 v[0:1], v[0:1], 0, v[4:5]
	global_load_dwordx4 v[80:83], v[2:3], off nt
	global_load_dwordx4 v[84:87], v[0:1], off nt
	v_add_u32_e32 v0, s16, v150
	v_ashrrev_i32_e32 v1, 31, v0
	v_add_u32_e32 v2, s16, v151
	v_lshlrev_b64 v[0:1], 12, v[0:1]
	v_ashrrev_i32_e32 v3, 31, v2
	v_lshl_add_u64 v[0:1], s[62:63], 0, v[0:1]
	s_lshl_b32 s4, s15, 8
	v_lshlrev_b64 v[2:3], 12, v[2:3]
	v_lshl_add_u64 v[0:1], v[0:1], 0, s[4:5]
	v_lshl_add_u64 v[2:3], s[62:63], 0, v[2:3]
	v_lshl_add_u64 v[0:1], v[0:1], 0, v[128:129]
	v_lshl_add_u64 v[2:3], v[2:3], 0, s[4:5]
	v_lshl_add_u64 v[2:3], v[2:3], 0, v[128:129]
	global_load_dwordx4 v[88:91], v[0:1], off offset:2048 nt
	global_load_dwordx4 v[92:95], v[2:3], off offset:2048 nt
	v_add_u32_e32 v0, s16, v152
	v_ashrrev_i32_e32 v1, 31, v0
	v_add_u32_e32 v2, s16, v153
	v_lshlrev_b64 v[0:1], 12, v[0:1]
	v_ashrrev_i32_e32 v3, 31, v2
	v_lshl_add_u64 v[0:1], s[62:63], 0, v[0:1]
	v_lshlrev_b64 v[2:3], 12, v[2:3]
	v_lshl_add_u64 v[0:1], v[0:1], 0, s[4:5]
	v_lshl_add_u64 v[2:3], s[62:63], 0, v[2:3]
	v_lshl_add_u64 v[0:1], v[0:1], 0, v[128:129]
	v_lshl_add_u64 v[2:3], v[2:3], 0, s[4:5]
	v_lshl_add_u64 v[2:3], v[2:3], 0, v[128:129]
	global_load_dwordx4 v[96:99], v[0:1], off offset:2048 nt
	global_load_dwordx4 v[100:103], v[2:3], off offset:2048 nt
	s_movk_i32 s4, 0x7f
	v_cmp_lt_i32_e64 s[4:5], s4, v120
	s_and_saveexec_b64 s[16:17], s[4:5]
	s_xor_b64 s[16:17], exec, s[16:17]
	s_cbranch_execz .LBB0_608
	s_movk_i32 s15, 0xc0
	v_cmp_gt_u32_e32 vcc, s15, v120
	s_and_saveexec_b64 s[18:19], vcc
	s_cbranch_execz .LBB0_607
	s_lshl_b64 s[22:23], s[6:7], 8
	s_add_u32 s22, s10, s22
	s_addc_u32 s23, s11, s23
	v_mov_b32_e32 v121, 0
	v_lshl_add_u64 v[0:1], v[120:121], 2, s[22:23]
	global_load_dword v123, v[0:1], off offset:-512 nt

.LBB0_608:
	s_or_saveexec_b64 s[16:17], s[16:17]
	v_ashrrev_i32_e32 v121, 31, v120
	s_xor_b64 exec, exec, s[16:17]
	s_cbranch_execz .LBB0_610
	s_ashr_i32 s15, s14, 31
	s_lshl_b64 s[18:19], s[14:15], 15
	s_add_u32 s15, s73, s18
	s_addc_u32 s19, s76, s19
	s_lshl_b32 s18, s20, 2
	s_add_u32 s18, s15, s18
	s_addc_u32 s19, s19, 0
	v_lshl_add_u64 v[0:1], v[120:121], 2, s[18:19]
	global_load_dword v123, v[0:1], off nt
.LBB0_610:
	s_or_b64 exec, exec, s[16:17]
	v_readlane_b32 s16, v247, 2
	s_sub_i32 s15, 7, s16
	s_cmpk_lt_u32 s79, 0x100
	s_cselect_b32 s16, s16, s15
	s_add_u32 s64, s46, 0xd00000
	s_addc_u32 s65, s47, 0
	s_add_u32 s66, s46, 0xe00000
	s_addc_u32 s67, s47, 0
	s_add_u32 s77, s46, 0xf04000
	s_addc_u32 s80, s47, 0
	s_ashr_i32 s15, s14, 31
	s_lshl_b32 s17, s16, 5
	s_lshl_b64 s[14:15], s[14:15], 13
	s_ashr_i32 s18, s17, 31
	s_or_b32 s14, s14, s20
	s_add_u32 s14, s14, s17
	v_and_b32_e32 v5, 31, v120
	s_addc_u32 s15, s15, s18
	v_or_b32_e32 v0, s14, v5
	v_mov_b32_e32 v1, s15
	v_lshlrev_b64 v[0:1], 2, v[0:1]
	s_lshl_b64 s[6:7], s[6:7], 2
	v_lshl_add_u64 v[2:3], s[64:65], 0, v[0:1]
	s_add_u32 s6, s77, s6
	s_waitcnt vmcnt(0)
	v_mov_b32_e32 v154, v123
	v_lshl_add_u64 v[0:1], s[66:67], 0, v[0:1]
	s_addc_u32 s7, s80, s7
	v_mov_b32_e32 v123, 0
	global_load_dword v187, v[2:3], off nt
	global_load_dword v33, v[0:1], off nt
	global_load_dword v32, v123, s[6:7] nt
	v_lshlrev_b32_e32 v0, 4, v120
	v_and_b32_e32 v1, 0x70, v0
	v_lshl_add_u64 v[130:131], s[12:13], 0, v[122:123]
	v_or_b32_e32 v136, s17, v5
	s_movk_i32 s13, 0x90
	v_add_u32_e32 v7, 0, v1
	v_mul_lo_u32 v1, v136, s13
	s_lshr_b32 s12, s79, 8
	v_add_u32_e32 v138, 0, v1
	v_mbcnt_lo_u32_b32 v1, -1, 0
	s_add_i32 s15, 0, 0x16400
	s_lshl_b32 s17, s12, 6
	v_mbcnt_hi_u32_b32 v1, -1, v1
	v_mov_b32_e32 v2, v120
	v_mov_b32_e32 v3, v123
	v_and_b32_e32 v10, 64, v1
	s_cmp_gt_i32 s16, -1
	v_bfe_u32 v6, v120, 5, 1
	v_lshl_add_u64 v[134:135], v[2:3], 2, s[10:11]
	v_xor_b32_e32 v9, 32, v1
	v_add_u32_e32 v10, 64, v10
	s_cselect_b64 s[70:71], -1, 0
	s_lshl_b32 s10, s12, 9
	v_and_b32_e32 v4, 63, v120
	v_mov_b32_e32 v129, v123
	v_cmp_lt_i32_e32 vcc, v9, v10
	v_lshlrev_b32_e32 v160, 2, v6
	s_add_i32 s10, s10, 0
	v_lshl_add_u64 v[132:133], s[8:9], 0, v[128:129]
	v_or_b32_e32 v2, s17, v5
	v_cndmask_b32_e32 v1, v1, v9, vcc
	v_cmp_gt_u32_e64 s[8:9], 32, v4
	v_lshl_add_u32 v161, v136, 2, s10
	s_movk_i32 s10, 0xff74
	v_or_b32_e32 v4, s17, v160
	s_movk_i32 s17, 0x110
	v_lshlrev_b32_e32 v159, 2, v1
	v_mad_u64_u32 v[140:141], s[10:11], v136, s10, v[138:139]
	v_mul_lo_u32 v1, v136, s17
	v_add_u32_e32 v141, s15, v1
	s_movk_i32 s10, 0x10c
	v_and_b32_e32 v0, 0xf0, v0
	v_mad_u64_u32 v[142:143], s[10:11], v136, s10, v[140:141]
	v_mov_b32_e32 v1, v123
	v_add_u32_e32 v156, 0, v0
	v_add_u32_e32 v157, s15, v0
	v_lshl_add_u64 v[0:1], s[46:47], 0, v[0:1]
	s_mov_b64 s[10:11], 0x8000000
	v_lshl_add_u64 v[144:145], v[0:1], 0, s[10:11]
	v_mul_lo_u32 v0, v147, s13
	v_mul_lo_u32 v1, v149, s13
	v_mul_lo_u32 v2, v2, s13
	s_add_i32 s13, 0, 0x1ec00
	v_lshlrev_b32_e32 v158, 4, v6
	v_lshlrev_b32_e32 v6, 3, v6
	v_lshlrev_b32_e32 v165, 1, v4
	v_lshl_add_u32 v173, v4, 2, s13
	s_mulk_i32 s12, 0x4200
	v_mul_u32_u24_e32 v4, 0x108, v5
	s_movk_i32 s10, 0x108
	v_add3_u32 v174, s12, v4, v6
	v_mul_u32_u24_e32 v4, 0x90, v5
	s_movk_i32 s12, 0x5000
	s_movk_i32 s14, 0xc0
	v_add_u32_e32 v3, 0, v158
	v_and_b32_e32 v8, 32, v120
	v_mul_lo_u32 v9, v150, s10
	v_mul_lo_u32 v10, v151, s10
	v_mul_lo_u32 v11, v152, s10
	v_mul_lo_u32 v12, v153, s10
	v_add3_u32 v175, v4, v158, s12
	s_mov_b32 s12, 0xe000
	v_cmp_gt_u32_e64 s[6:7], s14, v120
	s_mov_b32 s69, 0
	v_lshl_add_u32 v155, v120, 2, 0
	v_mov_b32_e32 v137, s18
	v_mul_lo_u32 v143, v150, s17
	v_mul_lo_u32 v162, v151, s17
	v_mul_lo_u32 v163, v152, s17
	v_mul_lo_u32 v164, v153, s17
	v_or_b32_e32 v166, 16, v165
	v_or_b32_e32 v167, 32, v165
	v_or_b32_e32 v168, 48, v165
	v_or_b32_e32 v169, 64, v165
	v_or_b32_e32 v170, 0x50, v165
	v_or_b32_e32 v171, 0x60, v165
	v_or_b32_e32 v172, 0x70, v165
	v_cmp_gt_i32_e64 s[10:11], s14, v120
	v_mov_b32_e32 v146, v136
	v_mov_b32_e32 v139, v136
	s_add_i32 s79, s16, 1
	v_add_u32_e32 v176, v7, v0
	v_add_u32_e32 v177, v7, v1
	v_add3_u32 v178, v156, v9, s12
	v_add3_u32 v179, v156, v10, s12
	v_add3_u32 v180, v156, v11, s12
	v_add3_u32 v181, v156, v12, s12
	v_add_u32_e32 v182, v3, v2
	v_add_u32_e32 v183, 0, v8
	s_mov_b32 s72, 0x3e000000
	v_mov_b32_e32 v184, 0x358637bd
	s_mov_b32 s81, 0x800000
	s_mov_b32 s52, s2
	s_branch .LBB0_612

.LBB0_612:
	s_barrier
	s_and_saveexec_b64 s[12:13], s[10:11]
	ds_write_b32 v155, v154
	s_or_b64 exec, exec, s[12:13]
	v_add_u32_e32 v0, v157, v143
	s_add_i32 s82, s52, s3
	ds_write_b128 v176, v[48:51] offset:2048
	ds_write_b128 v176, v[52:55] offset:20480
	ds_write_b128 v176, v[56:59] offset:38912
	ds_write_b128 v177, v[60:63] offset:2048
	ds_write_b128 v177, v[64:67] offset:20480
	ds_write_b128 v177, v[68:71] offset:38912
	ds_write2_b64 v178, v[72:73], v[74:75] offset1:1
	ds_write_b128 v0, v[88:91]
	ds_write2_b64 v179, v[76:77], v[78:79] offset1:1
	v_add_u32_e32 v0, v157, v162
	s_cmpk_gt_i32 s82, 0x7ff
	ds_write_b128 v0, v[92:95]
	ds_write2_b64 v180, v[80:81], v[82:83] offset1:1
	v_add_u32_e32 v0, v157, v163
	s_cselect_b64 s[74:75], -1, 0
	ds_write_b128 v0, v[96:99]
	ds_write2_b64 v181, v[84:85], v[86:87] offset1:1
	v_add_u32_e32 v0, v157, v164
	s_and_b64 vcc, exec, s[74:75]
	ds_write_b128 v0, v[100:103]
	s_waitcnt lgkmcnt(0)
	s_barrier
	s_cbranch_vccnz .LBB0_622
	s_lshl_b32 s12, s82, 6
	s_and_b32 s12, s12, 0x1c0
	s_and_b32 s13, s82, 0xfffffe00
	s_or_b32 s12, s12, s13
	s_bfe_u32 s13, s82, 0x60003
	s_lshl_b32 s15, s82, 4
	s_and_b32 s15, s15, 0xffffe000
	s_lshl_b32 s20, s13, 7
	s_or_b32 s16, s20, s15
	v_add_u32_e32 v2, s16, v147
	s_or_b32 s14, s12, s13
	s_ashr_i32 s12, s12, 6
	v_ashrrev_i32_e32 v3, 31, v2
	v_add_u32_e32 v4, s16, v149
	s_and_b32 s21, s12, 7
	v_lshlrev_b64 v[2:3], 12, v[2:3]
	v_ashrrev_i32_e32 v5, 31, v4
	s_ashr_i32 s15, s14, 31
	v_lshl_add_u64 v[2:3], s[62:63], 0, v[2:3]
	s_lshl_b32 s68, s21, 7
	v_lshlrev_b64 v[4:5], 12, v[4:5]
	s_lshl_b64 s[18:19], s[14:15], 14
	v_lshl_add_u64 v[2:3], v[2:3], 0, s[68:69]
	v_lshl_add_u64 v[4:5], s[62:63], 0, v[4:5]
	v_lshl_add_u64 v[0:1], v[130:131], 0, s[18:19]
	v_lshl_add_u64 v[2:3], v[2:3], 0, v[122:123]
	v_lshl_add_u64 v[4:5], v[4:5], 0, s[68:69]
	global_load_dwordx4 v[48:51], v[2:3], off nt
	global_load_dwordx4 v[52:55], v[2:3], off offset:1024 nt
	v_lshl_add_u64 v[2:3], v[124:125], 1, v[0:1]
	v_lshl_add_u64 v[4:5], v[4:5], 0, v[122:123]
	global_load_dwordx4 v[56:59], v[2:3], off nt
	global_load_dwordx4 v[60:63], v[4:5], off nt
	v_lshl_add_u64 v[0:1], v[126:127], 1, v[0:1]
	global_load_dwordx4 v[64:67], v[4:5], off offset:1024 nt
	global_load_dwordx4 v[68:71], v[0:1], off nt
	v_add_u32_e32 v2, s68, v150
	v_add_u32_e32 v4, s68, v151
	s_ashr_i32 s17, s16, 31
	v_ashrrev_i32_e32 v3, 31, v2
	v_ashrrev_i32_e32 v5, 31, v4
	v_lshl_add_u64 v[0:1], s[16:17], 1, v[132:133]
	v_lshlrev_b64 v[2:3], 16, v[2:3]
	v_lshlrev_b64 v[4:5], 16, v[4:5]
	v_lshl_add_u64 v[2:3], v[0:1], 0, v[2:3]
	v_lshl_add_u64 v[4:5], v[0:1], 0, v[4:5]
	global_load_dwordx4 v[72:75], v[2:3], off nt
	global_load_dwordx4 v[76:79], v[4:5], off nt
	v_add_u32_e32 v2, s68, v152
	v_add_u32_e32 v4, s68, v153
	v_ashrrev_i32_e32 v3, 31, v2
	v_ashrrev_i32_e32 v5, 31, v4
	v_lshlrev_b64 v[2:3], 16, v[2:3]
	v_lshlrev_b64 v[4:5], 16, v[4:5]
	v_lshl_add_u64 v[2:3], v[0:1], 0, v[2:3]
	v_lshl_add_u64 v[0:1], v[0:1], 0, v[4:5]
	global_load_dwordx4 v[80:83], v[2:3], off nt
	global_load_dwordx4 v[84:87], v[0:1], off nt
	v_add_u32_e32 v0, s16, v150
	v_ashrrev_i32_e32 v1, 31, v0
	v_add_u32_e32 v2, s16, v151
	v_lshlrev_b64 v[0:1], 12, v[0:1]
	v_ashrrev_i32_e32 v3, 31, v2
	v_lshl_add_u64 v[0:1], s[62:63], 0, v[0:1]
	s_lshl_b32 s68, s21, 8
	v_lshlrev_b64 v[2:3], 12, v[2:3]
	v_lshl_add_u64 v[0:1], v[0:1], 0, s[68:69]
	v_mov_b32_e32 v129, v123
	v_lshl_add_u64 v[2:3], s[62:63], 0, v[2:3]
	v_lshl_add_u64 v[0:1], v[0:1], 0, v[128:129]
	v_lshl_add_u64 v[2:3], v[2:3], 0, s[68:69]
	v_lshl_add_u64 v[2:3], v[2:3], 0, v[128:129]
	global_load_dwordx4 v[88:91], v[0:1], off offset:2048 nt
	global_load_dwordx4 v[92:95], v[2:3], off offset:2048 nt
	v_add_u32_e32 v0, s16, v152
	v_ashrrev_i32_e32 v1, 31, v0
	v_add_u32_e32 v2, s16, v153
	v_lshlrev_b64 v[0:1], 12, v[0:1]
	v_ashrrev_i32_e32 v3, 31, v2
	v_lshl_add_u64 v[0:1], s[62:63], 0, v[0:1]
	v_lshlrev_b64 v[2:3], 12, v[2:3]
	v_lshl_add_u64 v[0:1], v[0:1], 0, s[68:69]
	v_lshl_add_u64 v[2:3], s[62:63], 0, v[2:3]
	v_lshl_add_u64 v[0:1], v[0:1], 0, v[128:129]
	v_lshl_add_u64 v[2:3], v[2:3], 0, s[68:69]
	v_lshl_add_u64 v[2:3], v[2:3], 0, v[128:129]
	global_load_dwordx4 v[96:99], v[0:1], off offset:2048 nt
	global_load_dwordx4 v[100:103], v[2:3], off offset:2048 nt
	s_and_saveexec_b64 s[16:17], s[4:5]
	s_xor_b64 s[16:17], exec, s[16:17]
	s_cbranch_execz .LBB0_619
	s_and_saveexec_b64 s[18:19], s[6:7]
	s_cbranch_execz .LBB0_618
	s_lshl_b64 s[22:23], s[14:15], 8
	v_lshl_add_u64 v[0:1], v[134:135], 0, s[22:23]
	global_load_dword v154, v[0:1], off offset:-512 nt

.LBB0_619:
	s_andn2_saveexec_b64 s[16:17], s[16:17]
	s_cbranch_execz .LBB0_621
	s_ashr_i32 s13, s12, 31
	s_lshl_b64 s[18:19], s[12:13], 15
	s_add_u32 s13, s73, s18
	s_addc_u32 s19, s76, s19
	s_lshl_b32 s18, s20, 2
	s_add_u32 s18, s13, s18
	s_addc_u32 s19, s19, 0
	v_lshl_add_u64 v[0:1], v[120:121], 2, s[18:19]
	global_load_dword v154, v[0:1], off nt
.LBB0_621:
	s_or_b64 exec, exec, s[16:17]
	s_lshl_b64 s[14:15], s[14:15], 2
	s_add_u32 s14, s77, s14
	s_addc_u32 s15, s80, s15
	s_ashr_i32 s13, s12, 31
	s_lshl_b64 s[12:13], s[12:13], 13
	s_or_b32 s12, s12, s20
	v_lshl_add_u64 v[0:1], s[12:13], 0, v[136:137]
	v_lshlrev_b64 v[0:1], 2, v[0:1]
	v_lshl_add_u64 v[2:3], s[66:67], 0, v[0:1]
	v_lshl_add_u64 v[0:1], s[64:65], 0, v[0:1]
	global_load_dword v129, v123, s[14:15] nt
	global_load_dword v185, v[2:3], off nt
	global_load_dword v186, v[0:1], off nt
	s_branch .LBB0_623

.LBB0_1138:
	s_cmp_lt_i32 s48, 13
	s_cselect_b64 s[6:7], -1, 0
	s_and_b64 s[4:5], s[6:7], s[4:5]
	v_mov_b32_e32 v0, v190
	s_andn2_b64 vcc, exec, s[4:5]
	s_cbranch_vccnz .LBB0_1150
	s_lshl_b32 s6, s3, 3
	s_abs_i32 s7, s6
	v_cvt_f32_u32_e32 v1, s7
	s_sub_i32 s8, 0, s7
	s_ashr_i32 s6, s6, 31
	s_mov_b32 s27, 0
	v_rcp_iflag_f32_e32 v1, v1
	s_nop 0
	v_mul_f32_e32 v1, 0x4f7ffffe, v1
	v_cvt_u32_f32_e32 v1, v1
	s_nop 0
	v_readfirstlane_b32 s9, v1
	s_mul_i32 s8, s8, s9
	s_mul_hi_u32 s8, s9, s8
	s_add_i32 s9, s9, s8
	s_lshr_b32 s8, s9, 17
	s_mul_i32 s9, s8, s7
	s_sub_i32 s9, 0x8000, s9
	s_add_i32 s10, s8, 1
	s_sub_i32 s11, s9, s7
	s_cmp_ge_u32 s9, s7
	s_cselect_b32 s8, s10, s8
	s_cselect_b32 s9, s11, s9
	s_add_i32 s10, s8, 1
	s_cmp_ge_u32 s9, s7
	s_cselect_b32 s7, s10, s8
	s_xor_b32 s7, s7, s6
	s_sub_i32 s26, s7, s6
	s_cmp_lt_i32 s26, 1
	s_cbranch_scc1 .LBB0_1150
	s_load_dwordx2 s[8:9], s[0:1], 0x70
	s_load_dwordx2 s[10:11], s[0:1], 0x88
	v_and_b32_e32 v4, 63, v0
	v_lshlrev_b32_e32 v0, 4, v4
	v_lshlrev_b32_e32 v34, 3, v4
	s_waitcnt lgkmcnt(0)
	global_load_dwordx4 v[0:3], v0, s[8:9] nt
	s_nop 0
	global_load_dwordx2 v[8:9], v34, s[10:11] nt
	global_load_dwordx2 v[10:11], v34, s[10:11] offset:512 nt
	global_load_dwordx2 v[12:13], v34, s[10:11] offset:1024 nt
	v_mbcnt_lo_u32_b32 v5, -1, 0
	v_mbcnt_hi_u32_b32 v5, -1, v5
	v_and_b32_e32 v7, 64, v5
	v_add_u32_e32 v7, 64, v7
	v_xor_b32_e32 v16, 1, v5
	v_cmp_lt_i32_e32 vcc, v16, v7
	s_add_u32 s6, s46, 0x200000
	s_addc_u32 s7, s47, 0
	v_cndmask_b32_e32 v16, v5, v16, vcc
	v_lshlrev_b32_e32 v43, 2, v16
	v_xor_b32_e32 v16, 2, v5
	v_cmp_lt_i32_e32 vcc, v16, v7
	s_add_u32 s28, s46, 0x10000000
	s_addc_u32 s29, s47, 0
	v_cndmask_b32_e32 v16, v5, v16, vcc
	v_lshlrev_b32_e32 v45, 2, v16
	v_xor_b32_e32 v16, 4, v5
	s_add_u32 s8, s46, 0x600000
	v_cmp_lt_i32_e32 vcc, v16, v7
	v_mov_b32_e32 v6, 0
	s_addc_u32 s9, s47, 0
	s_lshl_b32 s0, s2, 3
	v_readlane_b32 s1, v247, 2
	v_cndmask_b32_e32 v16, v5, v16, vcc
	v_lshlrev_b32_e32 v36, 2, v4
	v_mov_b32_e32 v37, v6
	s_add_i32 s0, s1, s0
	v_lshlrev_b32_e32 v47, 2, v16
	v_xor_b32_e32 v16, 8, v5
	v_lshlrev_b32_e32 v28, 1, v4
	v_mov_b32_e32 v29, v6
	s_mul_i32 s12, s26, s0
	v_lshl_add_u64 v[18:19], s[46:47], 0, v[36:37]
	s_mov_b64 s[0:1], 0x12000000
	v_cmp_lt_i32_e32 vcc, v16, v7
	s_mov_b64 s[16:17], 0x15400000
	v_lshl_add_u64 v[14:15], v[18:19], 0, s[0:1]
	v_cndmask_b32_e32 v16, v5, v16, vcc
	v_lshl_add_u64 v[18:19], v[18:19], 0, s[16:17]
	v_lshl_add_u64 v[20:21], s[46:47], 0, v[28:29]
	s_mov_b64 s[16:17], 0x15000000
	s_ashr_i32 s13, s12, 31
	v_lshlrev_b32_e32 v50, 2, v16
	v_xor_b32_e32 v16, 16, v5
	v_lshl_add_u64 v[20:21], v[20:21], 0, s[16:17]
	s_lshl_b64 s[16:17], s[12:13], 7
	v_cmp_lt_i32_e32 vcc, v16, v7
	v_lshl_add_u64 v[22:23], s[16:17], 0, v[36:37]
	v_or_b32_e32 v24, s16, v28
	v_mov_b32_e32 v25, s17
	s_mul_hi_i32 s16, s12, 0x300
	s_mul_i32 s17, s12, 0x300
	v_cndmask_b32_e32 v16, v5, v16, vcc
	v_or_b32_e32 v26, s17, v36
	v_mov_b32_e32 v27, s16
	s_lshl_b64 s[16:17], s[12:13], 10
	s_mov_b64 s[10:11], 0x10000000
	v_lshlrev_b32_e32 v51, 2, v16
	v_xor_b32_e32 v16, 32, v5
	v_or_b32_e32 v30, s16, v34
	v_mov_b32_e32 v31, s17
	v_cmp_lt_i32_e32 vcc, v16, v7
	v_mov_b32_e32 v35, v6
	v_lshl_add_u64 v[30:31], v[30:31], 0, s[10:11]
	s_lshl_b64 s[10:11], s[12:13], 9
	v_cndmask_b32_e32 v5, v5, v16, vcc
	v_lshl_add_u64 v[16:17], s[46:47], 0, v[34:35]
	s_mov_b64 s[14:15], 0x14000000
	v_or_b32_e32 v34, s10, v34
	v_mov_b32_e32 v35, s11
	s_mov_b32 s10, 0x3b800000
	v_cmp_gt_u32_e64 s[0:1], 32, v4
	v_lshlrev_b32_e32 v52, 2, v5
	v_lshl_add_u64 v[16:17], v[16:17], 0, s[14:15]
	s_add_i32 s30, s12, 1
	v_or_b32_e32 v28, s16, v28
	v_mov_b32_e32 v29, s17
	v_or_b32_e32 v32, s16, v36
	v_mov_b32_e32 v33, s17
	v_lshl_add_u64 v[34:35], v[34:35], 0, s[14:15]
	v_lshlrev_b32_e32 v53, 1, v36
	v_mov_b32_e32 v36, 0x358637bd
	s_mov_b32 s11, 0x3b2aaaab
	s_mov_b32 s31, 0x800000
	s_mov_b32 s33, 0x15400000
	s_mov_b64 s[12:13], 0x100
	s_mov_b64 s[14:15], 0x600
	s_mov_b64 s[16:17], 0x800
	s_mov_b64 s[18:19], 0x400
	v_mov_b32_e32 v54, 0x300
	s_branch .LBB0_1142

.LBB0_1142:
	v_lshl_add_u64 v[40:41], s[46:47], 0, v[32:33]
	v_lshl_add_u64 v[38:39], s[46:47], 0, v[30:31]
	v_add_co_u32_e32 v40, vcc, 0x12000000, v40
	v_mov_b32_e32 v44, 0
	s_nop 0
	v_addc_co_u32_e32 v41, vcc, 0, v41, vcc
	global_load_dwordx2 v[48:49], v[38:39], off nt
	global_load_dword v60, v[40:41], off nt
	global_load_dword v59, v[40:41], off offset:256 nt
	global_load_dword v58, v[40:41], off offset:512 nt
	v_mov_b32_e32 v38, 0
	v_mov_b32_e32 v42, 0
	v_mov_b32_e32 v46, 0
	s_and_saveexec_b64 s[20:21], s[0:1]
	s_cbranch_execz .LBB0_1144
	v_lshl_add_u64 v[38:39], s[46:47], 0, v[28:29]
	v_add_co_u32_e32 v38, vcc, 0x10000000, v38
	v_lshl_add_u64 v[40:41], s[46:47], 0, v[22:23]
	s_nop 0
	v_addc_co_u32_e32 v39, vcc, 0, v39, vcc
	v_add_co_u32_e32 v56, vcc, 0x200000, v40
	s_nop 1
	v_addc_co_u32_e32 v57, vcc, 0, v41, vcc
	v_add_co_u32_e32 v40, vcc, 0x600000, v40
	s_nop 1
	v_addc_co_u32_e32 v41, vcc, 0, v41, vcc
	global_load_ushort v5, v[38:39], off offset:512 nt
	global_load_ushort v7, v[38:39], off offset:576 nt
	global_load_dword v42, v[56:57], off nt
	s_nop 0
	global_load_dword v38, v[40:41], off nt
	s_waitcnt vmcnt(0)
	v_lshlrev_b32_e32 v46, 16, v5
	v_lshlrev_b32_e32 v44, 16, v7
.LBB0_1144:
	s_or_b64 exec, exec, s[20:21]
	s_add_i32 s20, s30, s27
	s_ashr_i32 s21, s20, 31
	s_lshl_b64 s[24:25], s[20:21], 10
	s_add_u32 s22, s28, s24
	s_addc_u32 s23, s29, s25
	v_lshl_add_u64 v[62:63], v[14:15], 0, s[24:25]
	global_load_dwordx2 v[40:41], v53, s[22:23] nt
	global_load_dword v57, v[62:63], off nt
	global_load_dword v56, v[62:63], off offset:256 nt
	global_load_dword v55, v[62:63], off offset:512 nt
	v_mov_b32_e32 v5, v6
	v_mov_b32_e32 v39, v6
	v_mov_b32_e32 v7, v6
	v_mov_b32_e32 v37, v6
	s_and_saveexec_b64 s[24:25], s[0:1]
	s_cbranch_execz .LBB0_1146
	s_lshl_b64 s[34:35], s[20:21], 7
	v_lshlrev_b32_e32 v5, 1, v4
	v_lshl_or_b32 v62, v4, 2, s34
	v_mov_b32_e32 v63, s35
	v_lshl_add_u64 v[64:65], s[6:7], 0, v[62:63]
	v_lshl_add_u64 v[62:63], s[8:9], 0, v[62:63]
	global_load_ushort v39, v5, s[22:23] offset:512 nt
	global_load_ushort v61, v5, s[22:23] offset:576 nt
	global_load_dword v7, v[64:65], off nt
	global_load_dword v37, v[62:63], off nt
	s_waitcnt vmcnt(0)
	v_lshlrev_b32_e32 v5, 16, v39
	v_lshlrev_b32_e32 v39, 16, v61
